# RetQ epilogue: prefetch the 8 rope-table entries per round (no per-group store-ack wait)
# baseline (speedup 1.0000x reference)
; DI void st4(u16* p, float a, float b, float c, float d) { u32x2 w = {cvtpk(a, b), cvtpk(c, d)}; *(u32x2*)p = w; }
; DI float ex2(float x) { return __builtin_amdgcn_exp2f(x); }
;   DI void operator()(int m, int n, f32x4 v) const { st4(dst + (size_t)m * ld + n, v[0], v[1], v[2], v[3]); }
;   DI void operator()(int m, int n, f32x4 v) const {
;     const int tl = tok0 + m, pos = tl & 4095, tsc = pos & 255;
;     const int idx = (n < 128) ? (pos >> 6) : (pos & 63), f0 = (n >> 1) & 63;
;     const float2 c0 = tab[idx * 64 + f0], c1 = tab[idx * 64 + f0 + 1];
;     const float a0 = (v[0] * c0.x - v[1] * c0.y) * 0.0625f, b0 = (v[0] * c0.y + v[1] * c0.x) * 0.0625f;
;     const float a1 = (v[2] * c1.x - v[3] * c1.y) * 0.0625f, b1 = (v[2] * c1.y + v[3] * c1.x) * 0.0625f;
;     st4(qp + (size_t)tl * 1024 + hh * 256 + n, a0, b0, a1, b1);
;     const float qf = ex2(l2f * (float)(tsc + 1)), qb = ex2(l2b * (float)(256 - tsc));
;     u16* ac = acat + (size_t)tl * 3072 + hh * 768 + n;
;     st4(ac + 256, a0 * qf, b0 * qf, a1 * qf, b1 * qf);
;     st4(ac + 512, a0 * qb, b0 * qb, a1 * qb, b1 * qb);
;   }
.LBB0_259:
	v_cmp_gt_i32_e32 vcc, 3, v164
	s_movk_i32 s16, 0x2200
	v_mul_lo_u32 v128, v164, s16
	v_cndmask_b32_e32 v130, v143, v144, vcc
	v_add3_u32 v128, 16, v128, v130
	v_lshlrev_b32_e32 v132, 2, v136
	v_mul_u32_u24_e32 v133, 0x440, v160
	v_or_b32_e32 v131, v160, v161
	v_add3_u32 v132, v128, v132, v133
	ds_write2_b32 v132, v104, v108 offset1:16
	ds_write2_b32 v132, v105, v109 offset0:68 offset1:84
	ds_write2_b32 v132, v106, v110 offset0:136 offset1:152
	ds_write2_b32 v132, v107, v111 offset0:204 offset1:220
	ds_write2_b32 v132, v120, v124 offset0:32 offset1:48
	ds_write2_b32 v132, v121, v125 offset0:100 offset1:116
	ds_write2_b32 v132, v122, v126 offset0:168 offset1:184
	ds_write2_b32 v132, v123, v127 offset0:236 offset1:252
	v_add_u32_e32 v126, s34, v131
	v_and_b32_e32 v130, 28, v170
	v_cmp_gt_u32_e32 vcc, 8, v136
	v_lshrrev_b32_e32 v124, 6, v126
	v_lshlrev_b32_e32 v138, 4, v136
	v_lshl_or_b32 v130, v137, 5, v130
	s_movk_i32 s16, 0x80
	v_cndmask_b32_e32 v124, v160, v124, vcc
	v_and_or_b32 v150, v138, s16, v130
	v_lshrrev_b32_e32 v130, 1, v130
	v_add_u32_e32 v133, 0x1000, v132
	v_add_u32_e32 v137, 0x1400, v132
	v_lshlrev_b32_e32 v124, 6, v124
	ds_write2_b32 v133, v96, v100 offset0:64 offset1:80
	ds_write2_b32 v133, v97, v101 offset0:132 offset1:148
	ds_write2_b32 v133, v98, v102 offset0:200 offset1:216
	ds_write2_b32 v137, v99, v103 offset0:12 offset1:28
	ds_write2_b32 v133, v112, v116 offset0:96 offset1:112
	ds_write2_b32 v133, v113, v117 offset0:164 offset1:180
	ds_write2_b32 v133, v114, v118 offset0:232 offset1:248
	ds_write2_b32 v137, v115, v119 offset0:44 offset1:60
	v_mul_u32_u24_e32 v96, 0x110, v160
	v_and_or_b32 v124, v124, s29, v130
	s_waitcnt lgkmcnt(0)
	v_add3_u32 v136, v128, v138, v96
	v_lshlrev_b32_e32 v124, 3, v124
	ds_read_b128 v[138:141], v136
	ds_read_b128 v[120:123], v136 offset:1088
	ds_read_b128 v[116:119], v136 offset:2176
	ds_read_b128 v[112:115], v136 offset:3264
	ds_read_b128 v[108:111], v136 offset:4352
	ds_read_b128 v[104:107], v136 offset:5440
	ds_read_b128 v[100:103], v136 offset:6528
	ds_read_b128 v[96:99], v136 offset:7616
	v_and_b32_e32 v225, 8, v183
	v_lshlrev_b32_e32 v225, 8, v225
	global_load_dwordx4 v[192:195], v124, s[84:85]
	v_add_u32_e32 v224, v124, v225
	global_load_dwordx4 v[196:199], v224, s[84:85]
	v_add_u32_e32 v224, v224, v225
	global_load_dwordx4 v[200:203], v224, s[84:85]
	v_add_u32_e32 v224, v224, v225
	global_load_dwordx4 v[204:207], v224, s[84:85]
	v_add_u32_e32 v224, v224, v225
	global_load_dwordx4 v[208:211], v224, s[84:85]
	v_add_u32_e32 v224, v224, v225
	global_load_dwordx4 v[212:215], v224, s[84:85]
	v_add_u32_e32 v224, v224, v225
	global_load_dwordx4 v[216:219], v224, s[84:85]
	v_add_u32_e32 v224, v224, v225
	global_load_dwordx4 v[220:223], v224, s[84:85]
	s_lshl_b64 s[8:9], s[82:83], 1
	s_add_u32 s8, s89, s8
	v_ashrrev_i32_e32 v127, 31, v126
	s_addc_u32 s9, s21, s9
	s_movk_i32 s16, 0xc3
	v_lshlrev_b32_e32 v128, 1, v150
	v_bitop3_b32 v151, v160, s16, v161 bitop3:0xc8
	s_mulk_i32 s10, 0x300
	s_ashr_i32 s11, s10, 31
	s_lshl_b64 s[10:11], s[10:11], 1
	s_add_u32 s10, s24, s10
	s_addc_u32 s11, s25, s11
	s_waitcnt vmcnt(7) lgkmcnt(0)
	v_mov_b32_e32 v146, v192
	v_mov_b32_e32 v147, v193
	v_mov_b32_e32 v148, v194
	v_mov_b32_e32 v149, v195
	v_pk_mul_f32 v[124:125], v[138:139], v[146:147]
	s_nop 0
	v_sub_f32_e32 v124, v124, v125
	v_mul_f32_e32 v152, 0x3d800000, v124
	v_pk_mul_f32 v[124:125], v[138:139], v[146:147] op_sel:[1,0] op_sel_hi:[0,1]
	v_add_f32_e32 v124, v124, v125
	v_mul_f32_e32 v146, 0x3d800000, v124
	v_pk_mul_f32 v[124:125], v[140:141], v[148:149]
	v_cvt_pk_bf16_f32 v138, v152, v146
	s_nop 0
	v_sub_f32_e32 v124, v124, v125
	v_mul_f32_e32 v147, 0x3d800000, v124
	v_pk_mul_f32 v[124:125], v[140:141], v[148:149] op_sel:[1,0] op_sel_hi:[0,1]
	v_add_f32_e32 v124, v124, v125
	v_mul_f32_e32 v140, 0x3d800000, v124
	v_lshlrev_b64 v[124:125], 11, v[126:127]
	v_lshl_add_u64 v[124:125], s[8:9], 0, v[124:125]
	v_lshl_add_u64 v[124:125], v[124:125], 0, v[128:129]
	v_cvt_pk_bf16_f32 v139, v147, v140
	global_store_dwordx2 v[124:125], v[138:139], off
	v_add_u32_e32 v124, 1, v151
	v_cvt_f32_ubyte0_e32 v124, v124
	v_mul_f32_e32 v124, v135, v124
	v_exp_f32_e32 v138, v124
	v_sub_u32_e32 v124, 0x100, v151
	v_cvt_f32_u32_e32 v124, v124
	v_mul_f32_e32 v139, v138, v152
	v_mul_f32_e32 v148, v138, v146
	v_mul_f32_e32 v124, v134, v124
	v_exp_f32_e32 v141, v124
	v_mov_b64_e32 v[124:125], s[10:11]
	v_mad_i64_i32 v[126:127], s[10:11], v126, s28, v[124:125]
	v_lshl_add_u64 v[126:127], v[126:127], 0, v[128:129]
	v_mul_f32_e32 v149, v138, v147
	v_mul_f32_e32 v150, v138, v140
	v_cvt_pk_bf16_f32 v138, v139, v148
	v_cvt_pk_bf16_f32 v139, v149, v150
	global_store_dwordx2 v[126:127], v[138:139], off offset:512
	v_mul_f32_e32 v138, v141, v152
	v_mul_f32_e32 v139, v141, v146
	v_mul_f32_e32 v146, v141, v147
	v_mul_f32_e32 v140, v141, v140
	v_cvt_pk_bf16_f32 v138, v138, v139
	v_cvt_pk_bf16_f32 v139, v146, v140
	global_store_dwordx2 v[126:127], v[138:139], off offset:1024
	v_or_b32_e32 v127, 4, v131
	v_add_u32_e32 v126, s34, v127
	v_lshrrev_b32_e32 v138, 6, v126
	v_cndmask_b32_e32 v127, v127, v138, vcc
	v_lshlrev_b32_e32 v127, 6, v127
	v_and_or_b32 v127, v127, s29, v130
	v_lshlrev_b32_e32 v127, 3, v127
	s_movk_i32 s10, 0xc7
	v_bitop3_b32 v148, v131, s10, 4 bitop3:0xc8
	s_waitcnt vmcnt(9)
; DI void st4(u16* p, float a, float b, float c, float d) { u32x2 w = {cvtpk(a, b), cvtpk(c, d)}; *(u32x2*)p = w; }
; DI float ex2(float x) { return __builtin_amdgcn_exp2f(x); }
;   DI void operator()(int m, int n, f32x4 v) const { st4(dst + (size_t)m * ld + n, v[0], v[1], v[2], v[3]); }
;   DI void operator()(int m, int n, f32x4 v) const {
;     const int tl = tok0 + m, pos = tl & 4095, tsc = pos & 255;
;     const int idx = (n < 128) ? (pos >> 6) : (pos & 63), f0 = (n >> 1) & 63;
;     const float2 c0 = tab[idx * 64 + f0], c1 = tab[idx * 64 + f0 + 1];
;     const float a0 = (v[0] * c0.x - v[1] * c0.y) * 0.0625f, b0 = (v[0] * c0.y + v[1] * c0.x) * 0.0625f;
;     const float a1 = (v[2] * c1.x - v[3] * c1.y) * 0.0625f, b1 = (v[2] * c1.y + v[3] * c1.x) * 0.0625f;
;     st4(qp + (size_t)tl * 1024 + hh * 256 + n, a0, b0, a1, b1);
;     const float qf = ex2(l2f * (float)(tsc + 1)), qb = ex2(l2b * (float)(256 - tsc));
;     u16* ac = acat + (size_t)tl * 3072 + hh * 768 + n;
;     st4(ac + 256, a0 * qf, b0 * qf, a1 * qf, b1 * qf);
;     st4(ac + 512, a0 * qb, b0 * qb, a1 * qb, b1 * qb);
;   }
	v_mov_b32_e32 v138, v196
	v_mov_b32_e32 v139, v197
	v_mov_b32_e32 v140, v198
	v_mov_b32_e32 v141, v199
	v_pk_mul_f32 v[146:147], v[120:121], v[138:139]
	v_pk_mul_f32 v[120:121], v[120:121], v[138:139] op_sel:[1,0] op_sel_hi:[0,1]
	v_add_f32_e32 v120, v120, v121
	v_mul_f32_e32 v138, 0x3d800000, v120
	v_pk_mul_f32 v[120:121], v[122:123], v[140:141]
	v_sub_f32_e32 v127, v146, v147
	v_sub_f32_e32 v120, v120, v121
	v_mul_f32_e32 v139, 0x3d800000, v120
	v_pk_mul_f32 v[120:121], v[122:123], v[140:141] op_sel:[1,0] op_sel_hi:[0,1]
	v_mul_f32_e32 v146, 0x3d800000, v127
	v_add_f32_e32 v120, v120, v121
	v_ashrrev_i32_e32 v127, 31, v126
	v_mul_f32_e32 v140, 0x3d800000, v120
	v_lshlrev_b64 v[120:121], 11, v[126:127]
	v_lshl_add_u64 v[120:121], s[8:9], 0, v[120:121]
	v_lshl_add_u64 v[120:121], v[120:121], 0, v[128:129]
	v_cvt_pk_bf16_f32 v122, v146, v138
	v_cvt_pk_bf16_f32 v123, v139, v140
	global_store_dwordx2 v[120:121], v[122:123], off
	v_add_u32_e32 v120, 1, v148
	v_cvt_f32_ubyte0_e32 v120, v120
	v_mul_f32_e32 v120, v135, v120
	v_exp_f32_e32 v122, v120
	v_sub_u32_e32 v120, 0x100, v148
	v_cvt_f32_ubyte0_e32 v120, v120
	v_mul_f32_e32 v120, v134, v120
	v_exp_f32_e32 v127, v120
	v_mad_i64_i32 v[120:121], s[10:11], v126, s28, v[124:125]
	v_mul_f32_e32 v123, v122, v146
	v_lshl_add_u64 v[120:121], v[120:121], 0, v[128:129]
	v_mul_f32_e32 v126, v122, v138
	v_mul_f32_e32 v141, v122, v139
	v_mul_f32_e32 v147, v122, v140
	v_cvt_pk_bf16_f32 v122, v123, v126
	v_cvt_pk_bf16_f32 v123, v141, v147
	global_store_dwordx2 v[120:121], v[122:123], off offset:512
	v_mul_f32_e32 v122, v127, v146
	v_mul_f32_e32 v123, v127, v138
	v_mul_f32_e32 v126, v127, v139
	v_mul_f32_e32 v127, v127, v140
	v_cvt_pk_bf16_f32 v122, v122, v123
	v_cvt_pk_bf16_f32 v123, v126, v127
	global_store_dwordx2 v[120:121], v[122:123], off offset:1024
	v_or_b32_e32 v120, 8, v131
	v_add_u32_e32 v126, s34, v120
	v_lshrrev_b32_e32 v121, 6, v126
	v_cndmask_b32_e32 v120, v120, v121, vcc
	v_lshlrev_b32_e32 v120, 6, v120
	v_and_or_b32 v120, v120, s29, v130
	v_lshlrev_b32_e32 v120, 3, v120
	s_movk_i32 s10, 0xcb
	v_bitop3_b32 v140, v131, s10, 8 bitop3:0xc8
	s_waitcnt vmcnt(11)
	v_mov_b32_e32 v120, v200
	v_mov_b32_e32 v121, v201
	v_mov_b32_e32 v122, v202
	v_mov_b32_e32 v123, v203
	v_pk_mul_f32 v[138:139], v[116:117], v[120:121]
	v_pk_mul_f32 v[116:117], v[116:117], v[120:121] op_sel:[1,0] op_sel_hi:[0,1]
	v_add_f32_e32 v116, v116, v117
	v_mul_f32_e32 v120, 0x3d800000, v116
	v_pk_mul_f32 v[116:117], v[118:119], v[122:123]
	v_sub_f32_e32 v127, v138, v139
	v_sub_f32_e32 v116, v116, v117
	v_mul_f32_e32 v121, 0x3d800000, v116
	v_pk_mul_f32 v[116:117], v[118:119], v[122:123] op_sel:[1,0] op_sel_hi:[0,1]
	v_mul_f32_e32 v138, 0x3d800000, v127
	v_add_f32_e32 v116, v116, v117
	v_ashrrev_i32_e32 v127, 31, v126
	v_mul_f32_e32 v122, 0x3d800000, v116
	v_lshlrev_b64 v[116:117], 11, v[126:127]
	v_lshl_add_u64 v[116:117], s[8:9], 0, v[116:117]
	v_lshl_add_u64 v[116:117], v[116:117], 0, v[128:129]
	v_cvt_pk_bf16_f32 v118, v138, v120
	v_cvt_pk_bf16_f32 v119, v121, v122
	global_store_dwordx2 v[116:117], v[118:119], off
	v_add_u32_e32 v116, 1, v140
	v_cvt_f32_ubyte0_e32 v116, v116
	v_mul_f32_e32 v116, v135, v116
	v_exp_f32_e32 v118, v116
	v_sub_u32_e32 v116, 0x100, v140
	v_cvt_f32_ubyte0_e32 v116, v116
	v_mul_f32_e32 v116, v134, v116
	v_exp_f32_e32 v123, v116
	v_mad_i64_i32 v[116:117], s[10:11], v126, s28, v[124:125]
	v_mul_f32_e32 v119, v118, v138
	v_lshl_add_u64 v[116:117], v[116:117], 0, v[128:129]
	v_mul_f32_e32 v126, v118, v120
	v_mul_f32_e32 v127, v118, v121
	v_mul_f32_e32 v139, v118, v122
	v_cvt_pk_bf16_f32 v118, v119, v126
	v_cvt_pk_bf16_f32 v119, v127, v139
	global_store_dwordx2 v[116:117], v[118:119], off offset:512
	v_mul_f32_e32 v118, v123, v138
	v_mul_f32_e32 v119, v123, v120
	v_mul_f32_e32 v120, v123, v121
	v_mul_f32_e32 v121, v123, v122
	v_cvt_pk_bf16_f32 v118, v118, v119
	v_cvt_pk_bf16_f32 v119, v120, v121
	global_store_dwordx2 v[116:117], v[118:119], off offset:1024
	v_or_b32_e32 v116, 12, v131
	v_add_u32_e32 v120, s34, v116
	v_lshrrev_b32_e32 v117, 6, v120
	v_cndmask_b32_e32 v116, v116, v117, vcc
	v_lshlrev_b32_e32 v116, 6, v116
	v_and_or_b32 v116, v116, s29, v130
	v_lshlrev_b32_e32 v116, 3, v116
	s_movk_i32 s10, 0xcf
	v_bitop3_b32 v126, v131, s10, 12 bitop3:0xc8
	s_waitcnt vmcnt(13)
	v_mov_b32_e32 v116, v204
	v_mov_b32_e32 v117, v205
	v_mov_b32_e32 v118, v206
	v_mov_b32_e32 v119, v207
	v_pk_mul_f32 v[122:123], v[112:113], v[116:117]
	v_pk_mul_f32 v[112:113], v[112:113], v[116:117] op_sel:[1,0] op_sel_hi:[0,1]
	v_add_f32_e32 v112, v112, v113
	v_mul_f32_e32 v116, 0x3d800000, v112
	v_pk_mul_f32 v[112:113], v[114:115], v[118:119]
	v_sub_f32_e32 v121, v122, v123
	v_sub_f32_e32 v112, v112, v113
	v_mul_f32_e32 v117, 0x3d800000, v112
	v_pk_mul_f32 v[112:113], v[114:115], v[118:119] op_sel:[1,0] op_sel_hi:[0,1]
	v_mul_f32_e32 v122, 0x3d800000, v121
	v_add_f32_e32 v112, v112, v113
	v_ashrrev_i32_e32 v121, 31, v120
	v_mul_f32_e32 v118, 0x3d800000, v112
	v_lshlrev_b64 v[112:113], 11, v[120:121]
	v_lshl_add_u64 v[112:113], s[8:9], 0, v[112:113]
	v_lshl_add_u64 v[112:113], v[112:113], 0, v[128:129]
	v_cvt_pk_bf16_f32 v114, v122, v116
	v_cvt_pk_bf16_f32 v115, v117, v118
	global_store_dwordx2 v[112:113], v[114:115], off
	v_add_u32_e32 v112, 1, v126
	v_cvt_f32_ubyte0_e32 v112, v112
	v_mul_f32_e32 v112, v135, v112
	v_exp_f32_e32 v114, v112
	v_sub_u32_e32 v112, 0x100, v126
	v_cvt_f32_ubyte0_e32 v112, v112
	v_mul_f32_e32 v112, v134, v112
	v_exp_f32_e32 v119, v112
	v_mad_i64_i32 v[112:113], s[10:11], v120, s28, v[124:125]
	v_mul_f32_e32 v115, v114, v122
	v_lshl_add_u64 v[112:113], v[112:113], 0, v[128:129]
	v_mul_f32_e32 v120, v114, v116
	v_mul_f32_e32 v121, v114, v117
	v_mul_f32_e32 v123, v114, v118
	v_cvt_pk_bf16_f32 v114, v115, v120
	v_cvt_pk_bf16_f32 v115, v121, v123
	global_store_dwordx2 v[112:113], v[114:115], off offset:512
	v_mul_f32_e32 v114, v119, v122
	v_mul_f32_e32 v115, v119, v116
	v_mul_f32_e32 v116, v119, v117
	v_mul_f32_e32 v117, v119, v118
	v_cvt_pk_bf16_f32 v114, v114, v115
	v_cvt_pk_bf16_f32 v115, v116, v117
	global_store_dwordx2 v[112:113], v[114:115], off offset:1024
	v_or_b32_e32 v112, 16, v131
	v_add_u32_e32 v116, s34, v112
	v_lshrrev_b32_e32 v113, 6, v116
	v_cndmask_b32_e32 v112, v112, v113, vcc
	v_lshlrev_b32_e32 v112, 6, v112
	v_and_or_b32 v112, v112, s29, v130
	v_lshlrev_b32_e32 v112, 3, v112
	s_movk_i32 s10, 0xd3
	v_bitop3_b32 v120, v131, s10, 16 bitop3:0xc8
	s_waitcnt vmcnt(15)
; DI void st4(u16* p, float a, float b, float c, float d) { u32x2 w = {cvtpk(a, b), cvtpk(c, d)}; *(u32x2*)p = w; }
; DI float ex2(float x) { return __builtin_amdgcn_exp2f(x); }
;   DI void operator()(int m, int n, f32x4 v) const { st4(dst + (size_t)m * ld + n, v[0], v[1], v[2], v[3]); }
;   DI void operator()(int m, int n, f32x4 v) const {
;     const int tl = tok0 + m, pos = tl & 4095, tsc = pos & 255;
;     const int idx = (n < 128) ? (pos >> 6) : (pos & 63), f0 = (n >> 1) & 63;
;     const float2 c0 = tab[idx * 64 + f0], c1 = tab[idx * 64 + f0 + 1];
;     const float a0 = (v[0] * c0.x - v[1] * c0.y) * 0.0625f, b0 = (v[0] * c0.y + v[1] * c0.x) * 0.0625f;
;     const float a1 = (v[2] * c1.x - v[3] * c1.y) * 0.0625f, b1 = (v[2] * c1.y + v[3] * c1.x) * 0.0625f;
;     st4(qp + (size_t)tl * 1024 + hh * 256 + n, a0, b0, a1, b1);
;     const float qf = ex2(l2f * (float)(tsc + 1)), qb = ex2(l2b * (float)(256 - tsc));
;     u16* ac = acat + (size_t)tl * 3072 + hh * 768 + n;
;     st4(ac + 256, a0 * qf, b0 * qf, a1 * qf, b1 * qf);
;     st4(ac + 512, a0 * qb, b0 * qb, a1 * qb, b1 * qb);
;   }
	v_mov_b32_e32 v112, v208
	v_mov_b32_e32 v113, v209
	v_mov_b32_e32 v114, v210
	v_mov_b32_e32 v115, v211
	v_pk_mul_f32 v[118:119], v[108:109], v[112:113]
	v_pk_mul_f32 v[108:109], v[108:109], v[112:113] op_sel:[1,0] op_sel_hi:[0,1]
	v_add_f32_e32 v108, v108, v109
	v_mul_f32_e32 v112, 0x3d800000, v108
	v_pk_mul_f32 v[108:109], v[110:111], v[114:115]
	v_sub_f32_e32 v117, v118, v119
	v_sub_f32_e32 v108, v108, v109
	v_mul_f32_e32 v113, 0x3d800000, v108
	v_pk_mul_f32 v[108:109], v[110:111], v[114:115] op_sel:[1,0] op_sel_hi:[0,1]
	v_mul_f32_e32 v118, 0x3d800000, v117
	v_add_f32_e32 v108, v108, v109
	v_ashrrev_i32_e32 v117, 31, v116
	v_mul_f32_e32 v114, 0x3d800000, v108
	v_lshlrev_b64 v[108:109], 11, v[116:117]
	v_lshl_add_u64 v[108:109], s[8:9], 0, v[108:109]
	v_lshl_add_u64 v[108:109], v[108:109], 0, v[128:129]
	v_cvt_pk_bf16_f32 v110, v118, v112
	v_cvt_pk_bf16_f32 v111, v113, v114
	global_store_dwordx2 v[108:109], v[110:111], off
	v_add_u32_e32 v108, 1, v120
	v_cvt_f32_ubyte0_e32 v108, v108
	v_mul_f32_e32 v108, v135, v108
	v_exp_f32_e32 v110, v108
	v_sub_u32_e32 v108, 0x100, v120
	v_cvt_f32_ubyte0_e32 v108, v108
	v_mul_f32_e32 v108, v134, v108
	v_exp_f32_e32 v115, v108
	v_mad_i64_i32 v[108:109], s[10:11], v116, s28, v[124:125]
	v_mul_f32_e32 v111, v110, v118
	v_lshl_add_u64 v[108:109], v[108:109], 0, v[128:129]
	v_mul_f32_e32 v116, v110, v112
	v_mul_f32_e32 v117, v110, v113
	v_mul_f32_e32 v119, v110, v114
	v_cvt_pk_bf16_f32 v110, v111, v116
	v_cvt_pk_bf16_f32 v111, v117, v119
	global_store_dwordx2 v[108:109], v[110:111], off offset:512
	v_mul_f32_e32 v110, v115, v118
	v_mul_f32_e32 v111, v115, v112
	v_mul_f32_e32 v112, v115, v113
	v_mul_f32_e32 v113, v115, v114
	v_cvt_pk_bf16_f32 v110, v110, v111
	v_cvt_pk_bf16_f32 v111, v112, v113
	global_store_dwordx2 v[108:109], v[110:111], off offset:1024
	v_or_b32_e32 v108, 20, v131
	v_add_u32_e32 v112, s34, v108
	v_lshrrev_b32_e32 v109, 6, v112
	v_cndmask_b32_e32 v108, v108, v109, vcc
	v_lshlrev_b32_e32 v108, 6, v108
	v_and_or_b32 v108, v108, s29, v130
	v_lshlrev_b32_e32 v108, 3, v108
	s_movk_i32 s10, 0xd7
	v_bitop3_b32 v116, v131, s10, 20 bitop3:0xc8
	s_waitcnt vmcnt(17)
	v_mov_b32_e32 v108, v212
	v_mov_b32_e32 v109, v213
	v_mov_b32_e32 v110, v214
	v_mov_b32_e32 v111, v215
	v_pk_mul_f32 v[114:115], v[104:105], v[108:109]
	v_pk_mul_f32 v[104:105], v[104:105], v[108:109] op_sel:[1,0] op_sel_hi:[0,1]
	v_add_f32_e32 v104, v104, v105
	v_mul_f32_e32 v108, 0x3d800000, v104
	v_pk_mul_f32 v[104:105], v[106:107], v[110:111]
	v_sub_f32_e32 v113, v114, v115
	v_sub_f32_e32 v104, v104, v105
	v_mul_f32_e32 v109, 0x3d800000, v104
	v_pk_mul_f32 v[104:105], v[106:107], v[110:111] op_sel:[1,0] op_sel_hi:[0,1]
	v_mul_f32_e32 v114, 0x3d800000, v113
	v_add_f32_e32 v104, v104, v105
	v_ashrrev_i32_e32 v113, 31, v112
	v_mul_f32_e32 v110, 0x3d800000, v104
	v_lshlrev_b64 v[104:105], 11, v[112:113]
	v_lshl_add_u64 v[104:105], s[8:9], 0, v[104:105]
	v_lshl_add_u64 v[104:105], v[104:105], 0, v[128:129]
	v_cvt_pk_bf16_f32 v106, v114, v108
	v_cvt_pk_bf16_f32 v107, v109, v110
	global_store_dwordx2 v[104:105], v[106:107], off
	v_add_u32_e32 v104, 1, v116
	v_cvt_f32_ubyte0_e32 v104, v104
	v_mul_f32_e32 v104, v135, v104
	v_exp_f32_e32 v106, v104
	v_sub_u32_e32 v104, 0x100, v116
	v_cvt_f32_ubyte0_e32 v104, v104
	v_mul_f32_e32 v104, v134, v104
	v_exp_f32_e32 v111, v104
	v_mad_i64_i32 v[104:105], s[10:11], v112, s28, v[124:125]
	v_mul_f32_e32 v107, v106, v114
	v_lshl_add_u64 v[104:105], v[104:105], 0, v[128:129]
	v_mul_f32_e32 v112, v106, v108
	v_mul_f32_e32 v113, v106, v109
	v_mul_f32_e32 v115, v106, v110
	v_cvt_pk_bf16_f32 v106, v107, v112
	v_cvt_pk_bf16_f32 v107, v113, v115
	global_store_dwordx2 v[104:105], v[106:107], off offset:512
	v_mul_f32_e32 v106, v111, v114
	v_mul_f32_e32 v107, v111, v108
	v_mul_f32_e32 v108, v111, v109
	v_mul_f32_e32 v109, v111, v110
	v_cvt_pk_bf16_f32 v106, v106, v107
	v_cvt_pk_bf16_f32 v107, v108, v109
	global_store_dwordx2 v[104:105], v[106:107], off offset:1024
	v_or_b32_e32 v104, 24, v131
	v_add_u32_e32 v108, s34, v104
	v_lshrrev_b32_e32 v105, 6, v108
	v_cndmask_b32_e32 v104, v104, v105, vcc
	v_lshlrev_b32_e32 v104, 6, v104
	v_and_or_b32 v104, v104, s29, v130
	v_lshlrev_b32_e32 v104, 3, v104
	s_movk_i32 s10, 0xdb
	v_bitop3_b32 v112, v131, s10, 24 bitop3:0xc8
	s_waitcnt vmcnt(19)
	v_mov_b32_e32 v104, v216
	v_mov_b32_e32 v105, v217
	v_mov_b32_e32 v106, v218
	v_mov_b32_e32 v107, v219
	v_pk_mul_f32 v[110:111], v[100:101], v[104:105]
	v_pk_mul_f32 v[100:101], v[100:101], v[104:105] op_sel:[1,0] op_sel_hi:[0,1]
	v_add_f32_e32 v100, v100, v101
	v_mul_f32_e32 v104, 0x3d800000, v100
	v_pk_mul_f32 v[100:101], v[102:103], v[106:107]
	v_sub_f32_e32 v109, v110, v111
	v_sub_f32_e32 v100, v100, v101
	v_mul_f32_e32 v105, 0x3d800000, v100
	v_pk_mul_f32 v[100:101], v[102:103], v[106:107] op_sel:[1,0] op_sel_hi:[0,1]
	v_mul_f32_e32 v110, 0x3d800000, v109
	v_add_f32_e32 v100, v100, v101
	v_ashrrev_i32_e32 v109, 31, v108
	v_mul_f32_e32 v106, 0x3d800000, v100
	v_lshlrev_b64 v[100:101], 11, v[108:109]
	v_lshl_add_u64 v[100:101], s[8:9], 0, v[100:101]
	v_lshl_add_u64 v[100:101], v[100:101], 0, v[128:129]
	v_cvt_pk_bf16_f32 v102, v110, v104
	v_cvt_pk_bf16_f32 v103, v105, v106
	global_store_dwordx2 v[100:101], v[102:103], off
	v_add_u32_e32 v100, 1, v112
	v_cvt_f32_ubyte0_e32 v100, v100
	v_mul_f32_e32 v100, v135, v100
	v_exp_f32_e32 v102, v100
	v_sub_u32_e32 v100, 0x100, v112
	v_cvt_f32_ubyte0_e32 v100, v100
	v_mul_f32_e32 v100, v134, v100
	v_exp_f32_e32 v107, v100
	v_mad_i64_i32 v[100:101], s[10:11], v108, s28, v[124:125]
	v_mul_f32_e32 v103, v102, v110
	v_lshl_add_u64 v[100:101], v[100:101], 0, v[128:129]
	v_mul_f32_e32 v108, v102, v104
	v_mul_f32_e32 v109, v102, v105
	v_mul_f32_e32 v111, v102, v106
	v_cvt_pk_bf16_f32 v102, v103, v108
	v_cvt_pk_bf16_f32 v103, v109, v111
	global_store_dwordx2 v[100:101], v[102:103], off offset:512
	v_mul_f32_e32 v102, v107, v110
	v_mul_f32_e32 v103, v107, v104
	v_mul_f32_e32 v104, v107, v105
	v_mul_f32_e32 v105, v107, v106
	v_cvt_pk_bf16_f32 v102, v102, v103
	v_cvt_pk_bf16_f32 v103, v104, v105
	global_store_dwordx2 v[100:101], v[102:103], off offset:1024
	v_or_b32_e32 v100, 28, v131
	v_add_u32_e32 v104, s34, v100
	v_lshrrev_b32_e32 v101, 6, v104
	v_cndmask_b32_e32 v100, v100, v101, vcc
	v_lshlrev_b32_e32 v100, 6, v100
	v_and_or_b32 v100, v100, s29, v130
	v_lshlrev_b32_e32 v100, 3, v100
	s_movk_i32 s10, 0xdf
	v_bitop3_b32 v108, v131, s10, 28 bitop3:0xc8
	s_waitcnt vmcnt(21)
; DI void st4(u16* p, float a, float b, float c, float d) { u32x2 w = {cvtpk(a, b), cvtpk(c, d)}; *(u32x2*)p = w; }
; DI float ex2(float x) { return __builtin_amdgcn_exp2f(x); }
;   DI void operator()(int m, int n, f32x4 v) const { st4(dst + (size_t)m * ld + n, v[0], v[1], v[2], v[3]); }
;   DI void operator()(int m, int n, f32x4 v) const {
;     const int tl = tok0 + m, pos = tl & 4095, tsc = pos & 255;
;     const int idx = (n < 128) ? (pos >> 6) : (pos & 63), f0 = (n >> 1) & 63;
;     const float2 c0 = tab[idx * 64 + f0], c1 = tab[idx * 64 + f0 + 1];
;     const float a0 = (v[0] * c0.x - v[1] * c0.y) * 0.0625f, b0 = (v[0] * c0.y + v[1] * c0.x) * 0.0625f;
;     const float a1 = (v[2] * c1.x - v[3] * c1.y) * 0.0625f, b1 = (v[2] * c1.y + v[3] * c1.x) * 0.0625f;
;     st4(qp + (size_t)tl * 1024 + hh * 256 + n, a0, b0, a1, b1);
;     const float qf = ex2(l2f * (float)(tsc + 1)), qb = ex2(l2b * (float)(256 - tsc));
;     u16* ac = acat + (size_t)tl * 3072 + hh * 768 + n;
;     st4(ac + 256, a0 * qf, b0 * qf, a1 * qf, b1 * qf);
;     st4(ac + 512, a0 * qb, b0 * qb, a1 * qb, b1 * qb);
;   }
	v_mov_b32_e32 v100, v220
	v_mov_b32_e32 v101, v221
	v_mov_b32_e32 v102, v222
	v_mov_b32_e32 v103, v223
	v_pk_mul_f32 v[106:107], v[96:97], v[100:101]
	v_pk_mul_f32 v[96:97], v[96:97], v[100:101] op_sel:[1,0] op_sel_hi:[0,1]
	v_add_f32_e32 v96, v96, v97
	v_mul_f32_e32 v100, 0x3d800000, v96
	v_pk_mul_f32 v[96:97], v[98:99], v[102:103]
	v_sub_f32_e32 v105, v106, v107
	v_sub_f32_e32 v96, v96, v97
	v_mul_f32_e32 v101, 0x3d800000, v96
	v_pk_mul_f32 v[96:97], v[98:99], v[102:103] op_sel:[1,0] op_sel_hi:[0,1]
	v_mul_f32_e32 v106, 0x3d800000, v105
	v_add_f32_e32 v96, v96, v97
	v_ashrrev_i32_e32 v105, 31, v104
	v_mul_f32_e32 v102, 0x3d800000, v96
	v_lshlrev_b64 v[96:97], 11, v[104:105]
	v_lshl_add_u64 v[96:97], s[8:9], 0, v[96:97]
	v_lshl_add_u64 v[96:97], v[96:97], 0, v[128:129]
	v_cvt_pk_bf16_f32 v98, v106, v100
	v_cvt_pk_bf16_f32 v99, v101, v102
	global_store_dwordx2 v[96:97], v[98:99], off
	v_add_u32_e32 v96, 1, v108
	v_cvt_f32_ubyte0_e32 v96, v96
	v_mul_f32_e32 v96, v135, v96
	v_exp_f32_e32 v98, v96
	v_sub_u32_e32 v96, 0x100, v108
	v_cvt_f32_ubyte0_e32 v96, v96
	v_mul_f32_e32 v96, v134, v96
	v_exp_f32_e32 v103, v96
	v_mad_i64_i32 v[96:97], s[10:11], v104, s28, v[124:125]
	v_mul_f32_e32 v99, v98, v106
	v_lshl_add_u64 v[96:97], v[96:97], 0, v[128:129]
	v_mul_f32_e32 v104, v98, v100
	v_mul_f32_e32 v105, v98, v101
	v_mul_f32_e32 v107, v98, v102
	v_cvt_pk_bf16_f32 v98, v99, v104
	v_cvt_pk_bf16_f32 v99, v105, v107
	global_store_dwordx2 v[96:97], v[98:99], off offset:512
	v_mul_f32_e32 v98, v103, v106
	v_mul_f32_e32 v99, v103, v100
	v_mul_f32_e32 v100, v103, v101
	v_mul_f32_e32 v101, v103, v102
	v_cvt_pk_bf16_f32 v98, v98, v99
	v_cvt_pk_bf16_f32 v99, v100, v101
	global_store_dwordx2 v[96:97], v[98:99], off offset:1024
	v_or_b32_e32 v97, 32, v131
	v_add_u32_e32 v96, s34, v97
	v_lshrrev_b32_e32 v98, 6, v96
	v_cndmask_b32_e32 v97, v97, v98, vcc
	v_lshlrev_b32_e32 v97, 6, v97
	s_waitcnt lgkmcnt(0)
	ds_write2_b32 v132, v72, v76 offset1:16
	ds_write2_b32 v132, v73, v77 offset0:68 offset1:84
	ds_write2_b32 v132, v74, v78 offset0:136 offset1:152
	ds_write2_b32 v132, v75, v79 offset0:204 offset1:220
	ds_write2_b32 v132, v88, v92 offset0:32 offset1:48
	ds_write2_b32 v132, v89, v93 offset0:100 offset1:116
	ds_write2_b32 v132, v90, v94 offset0:168 offset1:184
	ds_write2_b32 v132, v91, v95 offset0:236 offset1:252
	ds_write2_b32 v133, v64, v68 offset0:64 offset1:80
	ds_write2_b32 v133, v65, v69 offset0:132 offset1:148
	ds_write2_b32 v133, v66, v70 offset0:200 offset1:216
	ds_write2_b32 v137, v67, v71 offset0:12 offset1:28
	ds_write2_b32 v133, v80, v84 offset0:96 offset1:112
	ds_write2_b32 v133, v81, v85 offset0:164 offset1:180
	ds_write2_b32 v133, v82, v86 offset0:232 offset1:248
	ds_write2_b32 v137, v83, v87 offset0:44 offset1:60
	v_and_or_b32 v97, v97, s29, v130
	s_waitcnt lgkmcnt(0)
	v_lshlrev_b32_e32 v97, 3, v97
	ds_read_b128 v[92:95], v136
	ds_read_b128 v[88:91], v136 offset:1088
	ds_read_b128 v[84:87], v136 offset:2176
	ds_read_b128 v[80:83], v136 offset:3264
	ds_read_b128 v[76:79], v136 offset:4352
	ds_read_b128 v[72:75], v136 offset:5440
	ds_read_b128 v[68:71], v136 offset:6528
	ds_read_b128 v[64:67], v136 offset:7616
	global_load_dwordx4 v[192:195], v97, s[84:85]
	v_add_u32_e32 v224, v97, v225
	global_load_dwordx4 v[196:199], v224, s[84:85]
	v_add_u32_e32 v224, v224, v225
	global_load_dwordx4 v[200:203], v224, s[84:85]
	v_add_u32_e32 v224, v224, v225
	global_load_dwordx4 v[204:207], v224, s[84:85]
	v_add_u32_e32 v224, v224, v225
	global_load_dwordx4 v[208:211], v224, s[84:85]
	v_add_u32_e32 v224, v224, v225
	global_load_dwordx4 v[212:215], v224, s[84:85]
	v_add_u32_e32 v224, v224, v225
	global_load_dwordx4 v[216:219], v224, s[84:85]
	v_add_u32_e32 v224, v224, v225
	global_load_dwordx4 v[220:223], v224, s[84:85]
	s_movk_i32 s10, 0xe3
	v_bitop3_b32 v104, v131, s10, 32 bitop3:0xc8
	s_waitcnt vmcnt(7) lgkmcnt(7)
	v_mov_b32_e32 v98, v192
	v_mov_b32_e32 v99, v193
	v_mov_b32_e32 v100, v194
	v_mov_b32_e32 v101, v195
	v_pk_mul_f32 v[102:103], v[92:93], v[98:99]
	v_pk_mul_f32 v[92:93], v[92:93], v[98:99] op_sel:[1,0] op_sel_hi:[0,1]
	v_add_f32_e32 v92, v92, v93
	v_mul_f32_e32 v98, 0x3d800000, v92
	v_pk_mul_f32 v[92:93], v[94:95], v[100:101]
	v_sub_f32_e32 v97, v102, v103
	v_sub_f32_e32 v92, v92, v93
	v_mul_f32_e32 v99, 0x3d800000, v92
	v_pk_mul_f32 v[92:93], v[94:95], v[100:101] op_sel:[1,0] op_sel_hi:[0,1]
	v_mul_f32_e32 v102, 0x3d800000, v97
	v_add_f32_e32 v92, v92, v93
	v_ashrrev_i32_e32 v97, 31, v96
	v_mul_f32_e32 v100, 0x3d800000, v92
	v_lshlrev_b64 v[92:93], 11, v[96:97]
	v_lshl_add_u64 v[92:93], s[8:9], 0, v[92:93]
	v_lshl_add_u64 v[92:93], v[92:93], 0, v[128:129]
	v_cvt_pk_bf16_f32 v94, v102, v98
	v_cvt_pk_bf16_f32 v95, v99, v100
	global_store_dwordx2 v[92:93], v[94:95], off
	v_add_u32_e32 v92, 1, v104
	v_cvt_f32_ubyte0_e32 v92, v92
	v_mul_f32_e32 v92, v135, v92
	v_exp_f32_e32 v94, v92
	v_sub_u32_e32 v92, 0x100, v104
	v_cvt_f32_ubyte0_e32 v92, v92
	v_mul_f32_e32 v92, v134, v92
	v_exp_f32_e32 v97, v92
	v_mad_i64_i32 v[92:93], s[10:11], v96, s28, v[124:125]
	v_mul_f32_e32 v95, v94, v102
	v_lshl_add_u64 v[92:93], v[92:93], 0, v[128:129]
	v_mul_f32_e32 v96, v94, v98
	v_mul_f32_e32 v101, v94, v99
	v_mul_f32_e32 v103, v94, v100
	v_cvt_pk_bf16_f32 v94, v95, v96
	v_cvt_pk_bf16_f32 v95, v101, v103
	global_store_dwordx2 v[92:93], v[94:95], off offset:512
	v_mul_f32_e32 v94, v97, v102
	v_mul_f32_e32 v95, v97, v98
	v_mul_f32_e32 v96, v97, v99
	v_mul_f32_e32 v97, v97, v100
	v_cvt_pk_bf16_f32 v94, v94, v95
	v_cvt_pk_bf16_f32 v95, v96, v97
	global_store_dwordx2 v[92:93], v[94:95], off offset:1024
	v_or_b32_e32 v92, 36, v131
	v_add_u32_e32 v96, s34, v92
	v_lshrrev_b32_e32 v93, 6, v96
	v_cndmask_b32_e32 v92, v92, v93, vcc
	v_lshlrev_b32_e32 v92, 6, v92
	v_and_or_b32 v92, v92, s29, v130
	v_lshlrev_b32_e32 v92, 3, v92
	s_movk_i32 s10, 0xe7
	v_bitop3_b32 v100, v131, s10, 36 bitop3:0xc8
	s_waitcnt vmcnt(9) lgkmcnt(6)
; DI void st4(u16* p, float a, float b, float c, float d) { u32x2 w = {cvtpk(a, b), cvtpk(c, d)}; *(u32x2*)p = w; }
; DI float ex2(float x) { return __builtin_amdgcn_exp2f(x); }
;   DI void operator()(int m, int n, f32x4 v) const { st4(dst + (size_t)m * ld + n, v[0], v[1], v[2], v[3]); }
;   DI void operator()(int m, int n, f32x4 v) const {
;     const int tl = tok0 + m, pos = tl & 4095, tsc = pos & 255;
;     const int idx = (n < 128) ? (pos >> 6) : (pos & 63), f0 = (n >> 1) & 63;
;     const float2 c0 = tab[idx * 64 + f0], c1 = tab[idx * 64 + f0 + 1];
;     const float a0 = (v[0] * c0.x - v[1] * c0.y) * 0.0625f, b0 = (v[0] * c0.y + v[1] * c0.x) * 0.0625f;
;     const float a1 = (v[2] * c1.x - v[3] * c1.y) * 0.0625f, b1 = (v[2] * c1.y + v[3] * c1.x) * 0.0625f;
;     st4(qp + (size_t)tl * 1024 + hh * 256 + n, a0, b0, a1, b1);
;     const float qf = ex2(l2f * (float)(tsc + 1)), qb = ex2(l2b * (float)(256 - tsc));
;     u16* ac = acat + (size_t)tl * 3072 + hh * 768 + n;
;     st4(ac + 256, a0 * qf, b0 * qf, a1 * qf, b1 * qf);
;     st4(ac + 512, a0 * qb, b0 * qb, a1 * qb, b1 * qb);
;   }
	v_mov_b32_e32 v92, v196
	v_mov_b32_e32 v93, v197
	v_mov_b32_e32 v94, v198
	v_mov_b32_e32 v95, v199
	v_pk_mul_f32 v[98:99], v[88:89], v[92:93]
	v_pk_mul_f32 v[88:89], v[88:89], v[92:93] op_sel:[1,0] op_sel_hi:[0,1]
	v_add_f32_e32 v88, v88, v89
	v_mul_f32_e32 v92, 0x3d800000, v88
	v_pk_mul_f32 v[88:89], v[90:91], v[94:95]
	v_sub_f32_e32 v97, v98, v99
	v_sub_f32_e32 v88, v88, v89
	v_mul_f32_e32 v93, 0x3d800000, v88
	v_pk_mul_f32 v[88:89], v[90:91], v[94:95] op_sel:[1,0] op_sel_hi:[0,1]
	v_mul_f32_e32 v98, 0x3d800000, v97
	v_add_f32_e32 v88, v88, v89
	v_ashrrev_i32_e32 v97, 31, v96
	v_mul_f32_e32 v94, 0x3d800000, v88
	v_lshlrev_b64 v[88:89], 11, v[96:97]
	v_lshl_add_u64 v[88:89], s[8:9], 0, v[88:89]
	v_lshl_add_u64 v[88:89], v[88:89], 0, v[128:129]
	v_cvt_pk_bf16_f32 v90, v98, v92
	v_cvt_pk_bf16_f32 v91, v93, v94
	global_store_dwordx2 v[88:89], v[90:91], off
	v_add_u32_e32 v88, 1, v100
	v_cvt_f32_ubyte0_e32 v88, v88
	v_mul_f32_e32 v88, v135, v88
	v_exp_f32_e32 v90, v88
	v_sub_u32_e32 v88, 0x100, v100
	v_cvt_f32_ubyte0_e32 v88, v88
	v_mul_f32_e32 v88, v134, v88
	v_exp_f32_e32 v95, v88
	v_mad_i64_i32 v[88:89], s[10:11], v96, s28, v[124:125]
	v_mul_f32_e32 v91, v90, v98
	v_lshl_add_u64 v[88:89], v[88:89], 0, v[128:129]
	v_mul_f32_e32 v96, v90, v92
	v_mul_f32_e32 v97, v90, v93
	v_mul_f32_e32 v99, v90, v94
	v_cvt_pk_bf16_f32 v90, v91, v96
	v_cvt_pk_bf16_f32 v91, v97, v99
	global_store_dwordx2 v[88:89], v[90:91], off offset:512
	v_mul_f32_e32 v90, v95, v98
	v_mul_f32_e32 v91, v95, v92
	v_mul_f32_e32 v92, v95, v93
	v_mul_f32_e32 v93, v95, v94
	v_cvt_pk_bf16_f32 v90, v90, v91
	v_cvt_pk_bf16_f32 v91, v92, v93
	global_store_dwordx2 v[88:89], v[90:91], off offset:1024
	v_or_b32_e32 v88, 40, v131
	v_add_u32_e32 v92, s34, v88
	v_lshrrev_b32_e32 v89, 6, v92
	v_cndmask_b32_e32 v88, v88, v89, vcc
	v_lshlrev_b32_e32 v88, 6, v88
	v_and_or_b32 v88, v88, s29, v130
	v_lshlrev_b32_e32 v88, 3, v88
	s_movk_i32 s10, 0xeb
	v_bitop3_b32 v96, v131, s10, 40 bitop3:0xc8
	s_waitcnt vmcnt(11) lgkmcnt(5)
	v_mov_b32_e32 v88, v200
	v_mov_b32_e32 v89, v201
	v_mov_b32_e32 v90, v202
	v_mov_b32_e32 v91, v203
	v_pk_mul_f32 v[94:95], v[84:85], v[88:89]
	v_pk_mul_f32 v[84:85], v[84:85], v[88:89] op_sel:[1,0] op_sel_hi:[0,1]
	v_add_f32_e32 v84, v84, v85
	v_mul_f32_e32 v88, 0x3d800000, v84
	v_pk_mul_f32 v[84:85], v[86:87], v[90:91]
	v_sub_f32_e32 v93, v94, v95
	v_sub_f32_e32 v84, v84, v85
	v_mul_f32_e32 v89, 0x3d800000, v84
	v_pk_mul_f32 v[84:85], v[86:87], v[90:91] op_sel:[1,0] op_sel_hi:[0,1]
	v_mul_f32_e32 v94, 0x3d800000, v93
	v_add_f32_e32 v84, v84, v85
	v_ashrrev_i32_e32 v93, 31, v92
	v_mul_f32_e32 v90, 0x3d800000, v84
	v_lshlrev_b64 v[84:85], 11, v[92:93]
	v_lshl_add_u64 v[84:85], s[8:9], 0, v[84:85]
	v_lshl_add_u64 v[84:85], v[84:85], 0, v[128:129]
	v_cvt_pk_bf16_f32 v86, v94, v88
	v_cvt_pk_bf16_f32 v87, v89, v90
	global_store_dwordx2 v[84:85], v[86:87], off
	v_add_u32_e32 v84, 1, v96
	v_cvt_f32_ubyte0_e32 v84, v84
	v_mul_f32_e32 v84, v135, v84
	v_exp_f32_e32 v86, v84
	v_sub_u32_e32 v84, 0x100, v96
	v_cvt_f32_ubyte0_e32 v84, v84
	v_mul_f32_e32 v84, v134, v84
	v_exp_f32_e32 v91, v84
	v_mad_i64_i32 v[84:85], s[10:11], v92, s28, v[124:125]
	v_mul_f32_e32 v87, v86, v94
	v_lshl_add_u64 v[84:85], v[84:85], 0, v[128:129]
	v_mul_f32_e32 v92, v86, v88
	v_mul_f32_e32 v93, v86, v89
	v_mul_f32_e32 v95, v86, v90
	v_cvt_pk_bf16_f32 v86, v87, v92
	v_cvt_pk_bf16_f32 v87, v93, v95
	global_store_dwordx2 v[84:85], v[86:87], off offset:512
	v_mul_f32_e32 v86, v91, v94
	v_mul_f32_e32 v87, v91, v88
	v_mul_f32_e32 v88, v91, v89
	v_mul_f32_e32 v89, v91, v90
	v_cvt_pk_bf16_f32 v86, v86, v87
	v_cvt_pk_bf16_f32 v87, v88, v89
	global_store_dwordx2 v[84:85], v[86:87], off offset:1024
	v_or_b32_e32 v84, 44, v131
	v_add_u32_e32 v88, s34, v84
	v_lshrrev_b32_e32 v85, 6, v88
	v_cndmask_b32_e32 v84, v84, v85, vcc
	v_lshlrev_b32_e32 v84, 6, v84
	v_and_or_b32 v84, v84, s29, v130
	v_lshlrev_b32_e32 v84, 3, v84
	s_movk_i32 s10, 0xef
	v_bitop3_b32 v92, v131, s10, 44 bitop3:0xc8
	s_waitcnt vmcnt(13) lgkmcnt(4)
	v_mov_b32_e32 v84, v204
	v_mov_b32_e32 v85, v205
	v_mov_b32_e32 v86, v206
	v_mov_b32_e32 v87, v207
	v_pk_mul_f32 v[90:91], v[80:81], v[84:85]
	v_pk_mul_f32 v[80:81], v[80:81], v[84:85] op_sel:[1,0] op_sel_hi:[0,1]
	v_add_f32_e32 v80, v80, v81
	v_mul_f32_e32 v84, 0x3d800000, v80
	v_pk_mul_f32 v[80:81], v[82:83], v[86:87]
	v_sub_f32_e32 v89, v90, v91
	v_sub_f32_e32 v80, v80, v81
	v_mul_f32_e32 v85, 0x3d800000, v80
	v_pk_mul_f32 v[80:81], v[82:83], v[86:87] op_sel:[1,0] op_sel_hi:[0,1]
	v_mul_f32_e32 v90, 0x3d800000, v89
	v_add_f32_e32 v80, v80, v81
	v_ashrrev_i32_e32 v89, 31, v88
	v_mul_f32_e32 v86, 0x3d800000, v80
	v_lshlrev_b64 v[80:81], 11, v[88:89]
	v_lshl_add_u64 v[80:81], s[8:9], 0, v[80:81]
	v_lshl_add_u64 v[80:81], v[80:81], 0, v[128:129]
	v_cvt_pk_bf16_f32 v82, v90, v84
	v_cvt_pk_bf16_f32 v83, v85, v86
	global_store_dwordx2 v[80:81], v[82:83], off
	v_add_u32_e32 v80, 1, v92
	v_cvt_f32_ubyte0_e32 v80, v80
	v_mul_f32_e32 v80, v135, v80
	v_exp_f32_e32 v82, v80
	v_sub_u32_e32 v80, 0x100, v92
	v_cvt_f32_ubyte0_e32 v80, v80
	v_mul_f32_e32 v80, v134, v80
	v_exp_f32_e32 v87, v80
	v_mad_i64_i32 v[80:81], s[10:11], v88, s28, v[124:125]
	v_mul_f32_e32 v83, v82, v90
	v_lshl_add_u64 v[80:81], v[80:81], 0, v[128:129]
	v_mul_f32_e32 v88, v82, v84
	v_mul_f32_e32 v89, v82, v85
	v_mul_f32_e32 v91, v82, v86
	v_cvt_pk_bf16_f32 v82, v83, v88
	v_cvt_pk_bf16_f32 v83, v89, v91
	global_store_dwordx2 v[80:81], v[82:83], off offset:512
	v_mul_f32_e32 v82, v87, v90
	v_mul_f32_e32 v83, v87, v84
	v_mul_f32_e32 v84, v87, v85
	v_mul_f32_e32 v85, v87, v86
	v_cvt_pk_bf16_f32 v82, v82, v83
	v_cvt_pk_bf16_f32 v83, v84, v85
	global_store_dwordx2 v[80:81], v[82:83], off offset:1024
	v_or_b32_e32 v80, 48, v131
	v_add_u32_e32 v84, s34, v80
	v_lshrrev_b32_e32 v81, 6, v84
	v_cndmask_b32_e32 v80, v80, v81, vcc
	v_lshlrev_b32_e32 v80, 6, v80
	v_and_or_b32 v80, v80, s29, v130
	v_lshlrev_b32_e32 v80, 3, v80
	s_movk_i32 s10, 0xf3
	v_bitop3_b32 v88, v131, s10, 48 bitop3:0xc8
	s_waitcnt vmcnt(15) lgkmcnt(3)
; DI void st4(u16* p, float a, float b, float c, float d) { u32x2 w = {cvtpk(a, b), cvtpk(c, d)}; *(u32x2*)p = w; }
; DI float ex2(float x) { return __builtin_amdgcn_exp2f(x); }
;   DI void operator()(int m, int n, f32x4 v) const { st4(dst + (size_t)m * ld + n, v[0], v[1], v[2], v[3]); }
;   DI void operator()(int m, int n, f32x4 v) const {
;     const int tl = tok0 + m, pos = tl & 4095, tsc = pos & 255;
;     const int idx = (n < 128) ? (pos >> 6) : (pos & 63), f0 = (n >> 1) & 63;
;     const float2 c0 = tab[idx * 64 + f0], c1 = tab[idx * 64 + f0 + 1];
;     const float a0 = (v[0] * c0.x - v[1] * c0.y) * 0.0625f, b0 = (v[0] * c0.y + v[1] * c0.x) * 0.0625f;
;     const float a1 = (v[2] * c1.x - v[3] * c1.y) * 0.0625f, b1 = (v[2] * c1.y + v[3] * c1.x) * 0.0625f;
;     st4(qp + (size_t)tl * 1024 + hh * 256 + n, a0, b0, a1, b1);
;     const float qf = ex2(l2f * (float)(tsc + 1)), qb = ex2(l2b * (float)(256 - tsc));
;     u16* ac = acat + (size_t)tl * 3072 + hh * 768 + n;
;     st4(ac + 256, a0 * qf, b0 * qf, a1 * qf, b1 * qf);
;     st4(ac + 512, a0 * qb, b0 * qb, a1 * qb, b1 * qb);
;   }
	v_mov_b32_e32 v80, v208
	v_mov_b32_e32 v81, v209
	v_mov_b32_e32 v82, v210
	v_mov_b32_e32 v83, v211
	v_pk_mul_f32 v[86:87], v[76:77], v[80:81]
	v_pk_mul_f32 v[76:77], v[76:77], v[80:81] op_sel:[1,0] op_sel_hi:[0,1]
	v_add_f32_e32 v76, v76, v77
	v_mul_f32_e32 v80, 0x3d800000, v76
	v_pk_mul_f32 v[76:77], v[78:79], v[82:83]
	v_sub_f32_e32 v85, v86, v87
	v_sub_f32_e32 v76, v76, v77
	v_mul_f32_e32 v81, 0x3d800000, v76
	v_pk_mul_f32 v[76:77], v[78:79], v[82:83] op_sel:[1,0] op_sel_hi:[0,1]
	v_mul_f32_e32 v86, 0x3d800000, v85
	v_add_f32_e32 v76, v76, v77
	v_ashrrev_i32_e32 v85, 31, v84
	v_mul_f32_e32 v82, 0x3d800000, v76
	v_lshlrev_b64 v[76:77], 11, v[84:85]
	v_lshl_add_u64 v[76:77], s[8:9], 0, v[76:77]
	v_lshl_add_u64 v[76:77], v[76:77], 0, v[128:129]
	v_cvt_pk_bf16_f32 v78, v86, v80
	v_cvt_pk_bf16_f32 v79, v81, v82
	global_store_dwordx2 v[76:77], v[78:79], off
	v_add_u32_e32 v76, 1, v88
	v_cvt_f32_ubyte0_e32 v76, v76
	v_mul_f32_e32 v76, v135, v76
	v_exp_f32_e32 v78, v76
	v_sub_u32_e32 v76, 0x100, v88
	v_cvt_f32_ubyte0_e32 v76, v76
	v_mul_f32_e32 v76, v134, v76
	v_exp_f32_e32 v83, v76
	v_mad_i64_i32 v[76:77], s[10:11], v84, s28, v[124:125]
	v_mul_f32_e32 v79, v78, v86
	v_lshl_add_u64 v[76:77], v[76:77], 0, v[128:129]
	v_mul_f32_e32 v84, v78, v80
	v_mul_f32_e32 v85, v78, v81
	v_mul_f32_e32 v87, v78, v82
	v_cvt_pk_bf16_f32 v78, v79, v84
	v_cvt_pk_bf16_f32 v79, v85, v87
	global_store_dwordx2 v[76:77], v[78:79], off offset:512
	v_mul_f32_e32 v78, v83, v86
	v_mul_f32_e32 v79, v83, v80
	v_mul_f32_e32 v80, v83, v81
	v_mul_f32_e32 v81, v83, v82
	v_cvt_pk_bf16_f32 v78, v78, v79
	v_cvt_pk_bf16_f32 v79, v80, v81
	global_store_dwordx2 v[76:77], v[78:79], off offset:1024
	v_or_b32_e32 v76, 52, v131
	v_add_u32_e32 v80, s34, v76
	v_lshrrev_b32_e32 v77, 6, v80
	v_cndmask_b32_e32 v76, v76, v77, vcc
	v_lshlrev_b32_e32 v76, 6, v76
	v_and_or_b32 v76, v76, s29, v130
	v_lshlrev_b32_e32 v76, 3, v76
	s_movk_i32 s10, 0xf7
	v_bitop3_b32 v84, v131, s10, 52 bitop3:0xc8
	s_waitcnt vmcnt(17) lgkmcnt(2)
	v_mov_b32_e32 v76, v212
	v_mov_b32_e32 v77, v213
	v_mov_b32_e32 v78, v214
	v_mov_b32_e32 v79, v215
	v_pk_mul_f32 v[82:83], v[72:73], v[76:77]
	v_pk_mul_f32 v[72:73], v[72:73], v[76:77] op_sel:[1,0] op_sel_hi:[0,1]
	v_add_f32_e32 v72, v72, v73
	v_mul_f32_e32 v76, 0x3d800000, v72
	v_pk_mul_f32 v[72:73], v[74:75], v[78:79]
	v_sub_f32_e32 v81, v82, v83
	v_sub_f32_e32 v72, v72, v73
	v_mul_f32_e32 v77, 0x3d800000, v72
	v_pk_mul_f32 v[72:73], v[74:75], v[78:79] op_sel:[1,0] op_sel_hi:[0,1]
	v_mul_f32_e32 v82, 0x3d800000, v81
	v_add_f32_e32 v72, v72, v73
	v_ashrrev_i32_e32 v81, 31, v80
	v_mul_f32_e32 v78, 0x3d800000, v72
	v_lshlrev_b64 v[72:73], 11, v[80:81]
	v_lshl_add_u64 v[72:73], s[8:9], 0, v[72:73]
	v_lshl_add_u64 v[72:73], v[72:73], 0, v[128:129]
	v_cvt_pk_bf16_f32 v74, v82, v76
	v_cvt_pk_bf16_f32 v75, v77, v78
	global_store_dwordx2 v[72:73], v[74:75], off
	v_add_u32_e32 v72, 1, v84
	v_cvt_f32_ubyte0_e32 v72, v72
	v_mul_f32_e32 v72, v135, v72
	v_exp_f32_e32 v74, v72
	v_sub_u32_e32 v72, 0x100, v84
	v_cvt_f32_ubyte0_e32 v72, v72
	v_mul_f32_e32 v72, v134, v72
	v_exp_f32_e32 v79, v72
	v_mad_i64_i32 v[72:73], s[10:11], v80, s28, v[124:125]
	v_mul_f32_e32 v75, v74, v82
	v_lshl_add_u64 v[72:73], v[72:73], 0, v[128:129]
	v_mul_f32_e32 v80, v74, v76
	v_mul_f32_e32 v81, v74, v77
	v_mul_f32_e32 v83, v74, v78
	v_cvt_pk_bf16_f32 v74, v75, v80
	v_cvt_pk_bf16_f32 v75, v81, v83
	global_store_dwordx2 v[72:73], v[74:75], off offset:512
	v_mul_f32_e32 v74, v79, v82
	v_mul_f32_e32 v75, v79, v76
	v_mul_f32_e32 v76, v79, v77
	v_mul_f32_e32 v77, v79, v78
	v_cvt_pk_bf16_f32 v74, v74, v75
	v_cvt_pk_bf16_f32 v75, v76, v77
	global_store_dwordx2 v[72:73], v[74:75], off offset:1024
	v_or_b32_e32 v72, 56, v131
	v_add_u32_e32 v76, s34, v72
	v_lshrrev_b32_e32 v73, 6, v76
	v_cndmask_b32_e32 v72, v72, v73, vcc
	v_lshlrev_b32_e32 v72, 6, v72
	v_and_or_b32 v72, v72, s29, v130
	v_lshlrev_b32_e32 v72, 3, v72
	s_movk_i32 s10, 0xfb
	v_bitop3_b32 v80, v131, s10, 56 bitop3:0xc8
	s_waitcnt vmcnt(19) lgkmcnt(1)
	v_mov_b32_e32 v72, v216
	v_mov_b32_e32 v73, v217
	v_mov_b32_e32 v74, v218
	v_mov_b32_e32 v75, v219
	v_pk_mul_f32 v[78:79], v[68:69], v[72:73]
	v_pk_mul_f32 v[68:69], v[68:69], v[72:73] op_sel:[1,0] op_sel_hi:[0,1]
	v_add_f32_e32 v68, v68, v69
	v_mul_f32_e32 v72, 0x3d800000, v68
	v_pk_mul_f32 v[68:69], v[70:71], v[74:75]
	v_sub_f32_e32 v77, v78, v79
	v_sub_f32_e32 v68, v68, v69
	v_mul_f32_e32 v73, 0x3d800000, v68
	v_pk_mul_f32 v[68:69], v[70:71], v[74:75] op_sel:[1,0] op_sel_hi:[0,1]
	v_mul_f32_e32 v78, 0x3d800000, v77
	v_add_f32_e32 v68, v68, v69
	v_ashrrev_i32_e32 v77, 31, v76
	v_mul_f32_e32 v74, 0x3d800000, v68
	v_lshlrev_b64 v[68:69], 11, v[76:77]
	v_lshl_add_u64 v[68:69], s[8:9], 0, v[68:69]
	v_lshl_add_u64 v[68:69], v[68:69], 0, v[128:129]
	v_cvt_pk_bf16_f32 v70, v78, v72
	v_cvt_pk_bf16_f32 v71, v73, v74
	global_store_dwordx2 v[68:69], v[70:71], off
	v_add_u32_e32 v68, 1, v80
	v_cvt_f32_ubyte0_e32 v68, v68
	v_mul_f32_e32 v68, v135, v68
	v_exp_f32_e32 v70, v68
	v_sub_u32_e32 v68, 0x100, v80
	v_cvt_f32_ubyte0_e32 v68, v68
	v_mul_f32_e32 v68, v134, v68
	v_exp_f32_e32 v75, v68
	v_mad_i64_i32 v[68:69], s[10:11], v76, s28, v[124:125]
	v_mul_f32_e32 v71, v70, v78
	v_lshl_add_u64 v[68:69], v[68:69], 0, v[128:129]
	v_mul_f32_e32 v76, v70, v72
	v_mul_f32_e32 v77, v70, v73
	v_mul_f32_e32 v79, v70, v74
	v_cvt_pk_bf16_f32 v70, v71, v76
	v_cvt_pk_bf16_f32 v71, v77, v79
	global_store_dwordx2 v[68:69], v[70:71], off offset:512
	v_mul_f32_e32 v70, v75, v78
	v_mul_f32_e32 v71, v75, v72
	v_mul_f32_e32 v72, v75, v73
	v_or_b32_e32 v76, 60, v131
	v_mul_f32_e32 v73, v75, v74
	v_cvt_pk_bf16_f32 v70, v70, v71
	v_cvt_pk_bf16_f32 v71, v72, v73
	v_add_u32_e32 v72, s34, v76
	global_store_dwordx2 v[68:69], v[70:71], off offset:1024
	v_lshrrev_b32_e32 v68, 6, v72
	v_cndmask_b32_e32 v68, v76, v68, vcc
	v_lshlrev_b32_e32 v68, 6, v68
	v_and_or_b32 v68, v68, s29, v130
	v_lshlrev_b32_e32 v68, 3, v68
	s_movk_i32 s10, 0xff
	v_bitop3_b32 v77, v131, s10, 60 bitop3:0xc8
	s_waitcnt vmcnt(21) lgkmcnt(0)
; DI void st4(u16* p, float a, float b, float c, float d) { u32x2 w = {cvtpk(a, b), cvtpk(c, d)}; *(u32x2*)p = w; }
; DI float ex2(float x) { return __builtin_amdgcn_exp2f(x); }
;   DI void operator()(int m, int n, f32x4 v) const { st4(dst + (size_t)m * ld + n, v[0], v[1], v[2], v[3]); }
;   DI void operator()(int m, int n, f32x4 v) const {
;     const int tl = tok0 + m, pos = tl & 4095, tsc = pos & 255;
;     const int idx = (n < 128) ? (pos >> 6) : (pos & 63), f0 = (n >> 1) & 63;
;     const float2 c0 = tab[idx * 64 + f0], c1 = tab[idx * 64 + f0 + 1];
;     const float a0 = (v[0] * c0.x - v[1] * c0.y) * 0.0625f, b0 = (v[0] * c0.y + v[1] * c0.x) * 0.0625f;
;     const float a1 = (v[2] * c1.x - v[3] * c1.y) * 0.0625f, b1 = (v[2] * c1.y + v[3] * c1.x) * 0.0625f;
;     st4(qp + (size_t)tl * 1024 + hh * 256 + n, a0, b0, a1, b1);
;     const float qf = ex2(l2f * (float)(tsc + 1)), qb = ex2(l2b * (float)(256 - tsc));
;     u16* ac = acat + (size_t)tl * 3072 + hh * 768 + n;
;     st4(ac + 256, a0 * qf, b0 * qf, a1 * qf, b1 * qf);
;     st4(ac + 512, a0 * qb, b0 * qb, a1 * qb, b1 * qb);
;   }
	v_mov_b32_e32 v68, v220
	v_mov_b32_e32 v69, v221
	v_mov_b32_e32 v70, v222
	v_mov_b32_e32 v71, v223
	v_pk_mul_f32 v[74:75], v[64:65], v[68:69]
	v_pk_mul_f32 v[64:65], v[64:65], v[68:69] op_sel:[1,0] op_sel_hi:[0,1]
	v_add_f32_e32 v64, v64, v65
	v_mul_f32_e32 v68, 0x3d800000, v64
	v_pk_mul_f32 v[64:65], v[66:67], v[70:71]
	v_sub_f32_e32 v73, v74, v75
	v_sub_f32_e32 v64, v64, v65
	v_mul_f32_e32 v69, 0x3d800000, v64
	v_pk_mul_f32 v[64:65], v[66:67], v[70:71] op_sel:[1,0] op_sel_hi:[0,1]
	v_mul_f32_e32 v74, 0x3d800000, v73
	v_add_f32_e32 v64, v64, v65
	v_ashrrev_i32_e32 v73, 31, v72
	v_mul_f32_e32 v70, 0x3d800000, v64
	v_lshlrev_b64 v[64:65], 11, v[72:73]
	v_lshl_add_u64 v[64:65], s[8:9], 0, v[64:65]
	v_lshl_add_u64 v[64:65], v[64:65], 0, v[128:129]
	v_cvt_pk_bf16_f32 v66, v74, v68
	v_cvt_pk_bf16_f32 v67, v69, v70
	global_store_dwordx2 v[64:65], v[66:67], off
	v_add_u32_e32 v64, 1, v77
	v_cvt_f32_u32_e32 v64, v64
	v_mul_f32_e32 v64, v135, v64
	v_exp_f32_e32 v66, v64
	v_sub_u32_e32 v64, 0x100, v76
	v_cvt_f32_ubyte0_e32 v64, v64
	v_mul_f32_e32 v64, v134, v64
	v_exp_f32_e32 v71, v64
	v_mad_i64_i32 v[64:65], s[10:11], v72, s28, v[124:125]
	v_mul_f32_e32 v67, v66, v74
	v_lshl_add_u64 v[64:65], v[64:65], 0, v[128:129]
	v_mul_f32_e32 v72, v66, v68
	v_mul_f32_e32 v73, v66, v69
	v_mul_f32_e32 v75, v66, v70
	v_cvt_pk_bf16_f32 v66, v67, v72
	v_cvt_pk_bf16_f32 v67, v73, v75
	global_store_dwordx2 v[64:65], v[66:67], off offset:512
	v_mul_f32_e32 v66, v71, v74
	v_mul_f32_e32 v67, v71, v68
	v_mul_f32_e32 v68, v71, v69
	v_mul_f32_e32 v69, v71, v70
	v_cvt_pk_bf16_f32 v66, v66, v67
	v_cvt_pk_bf16_f32 v67, v68, v69
	global_store_dwordx2 v[64:65], v[66:67], off offset:1024
	v_add_u32_e32 v65, 0x80, v131
	v_add_u32_e32 v64, s34, v65
	v_and_b32_e32 v72, 0xc3, v65
	v_lshrrev_b32_e32 v65, 6, v64
	v_cndmask_b32_e32 v65, v160, v65, vcc
	v_lshlrev_b32_e32 v65, 6, v65
	s_waitcnt lgkmcnt(0)
	ds_write2_b32 v132, v40, v44 offset1:16
	ds_write2_b32 v132, v41, v45 offset0:68 offset1:84
	ds_write2_b32 v132, v42, v46 offset0:136 offset1:152
	ds_write2_b32 v132, v43, v47 offset0:204 offset1:220
	ds_write2_b32 v132, v56, v60 offset0:32 offset1:48
	ds_write2_b32 v132, v57, v61 offset0:100 offset1:116
	ds_write2_b32 v132, v58, v62 offset0:168 offset1:184
	ds_write2_b32 v132, v59, v63 offset0:236 offset1:252
	ds_write2_b32 v133, v32, v36 offset0:64 offset1:80
	ds_write2_b32 v133, v33, v37 offset0:132 offset1:148
	ds_write2_b32 v133, v34, v38 offset0:200 offset1:216
	ds_write2_b32 v137, v35, v39 offset0:12 offset1:28
	ds_write2_b32 v133, v48, v52 offset0:96 offset1:112
	ds_write2_b32 v133, v49, v53 offset0:164 offset1:180
	ds_write2_b32 v133, v50, v54 offset0:232 offset1:248
	ds_write2_b32 v137, v51, v55 offset0:44 offset1:60
	v_and_or_b32 v65, v65, s29, v130
	s_waitcnt lgkmcnt(0)
	v_lshlrev_b32_e32 v65, 3, v65
	ds_read_b128 v[60:63], v136
	ds_read_b128 v[56:59], v136 offset:1088
	ds_read_b128 v[52:55], v136 offset:2176
	ds_read_b128 v[48:51], v136 offset:3264
	ds_read_b128 v[44:47], v136 offset:4352
	ds_read_b128 v[40:43], v136 offset:5440
	ds_read_b128 v[36:39], v136 offset:6528
	ds_read_b128 v[32:35], v136 offset:7616
	global_load_dwordx4 v[192:195], v65, s[84:85]
	v_add_u32_e32 v224, v65, v225
	global_load_dwordx4 v[196:199], v224, s[84:85]
	v_add_u32_e32 v224, v224, v225
	global_load_dwordx4 v[200:203], v224, s[84:85]
	v_add_u32_e32 v224, v224, v225
	global_load_dwordx4 v[204:207], v224, s[84:85]
	v_add_u32_e32 v224, v224, v225
	global_load_dwordx4 v[208:211], v224, s[84:85]
	v_add_u32_e32 v224, v224, v225
	global_load_dwordx4 v[212:215], v224, s[84:85]
	v_add_u32_e32 v224, v224, v225
	global_load_dwordx4 v[216:219], v224, s[84:85]
	v_add_u32_e32 v224, v224, v225
	global_load_dwordx4 v[220:223], v224, s[84:85]
	s_waitcnt vmcnt(7) lgkmcnt(7)
	v_mov_b32_e32 v66, v192
	v_mov_b32_e32 v67, v193
	v_mov_b32_e32 v68, v194
	v_mov_b32_e32 v69, v195
	v_pk_mul_f32 v[70:71], v[60:61], v[66:67]
	v_pk_mul_f32 v[60:61], v[60:61], v[66:67] op_sel:[1,0] op_sel_hi:[0,1]
	v_add_f32_e32 v60, v60, v61
	v_mul_f32_e32 v66, 0x3d800000, v60
	v_pk_mul_f32 v[60:61], v[62:63], v[68:69]
	v_sub_f32_e32 v65, v70, v71
	v_sub_f32_e32 v60, v60, v61
	v_mul_f32_e32 v67, 0x3d800000, v60
	v_pk_mul_f32 v[60:61], v[62:63], v[68:69] op_sel:[1,0] op_sel_hi:[0,1]
	v_mul_f32_e32 v70, 0x3d800000, v65
	v_add_f32_e32 v60, v60, v61
	v_ashrrev_i32_e32 v65, 31, v64
	v_mul_f32_e32 v68, 0x3d800000, v60
	v_lshlrev_b64 v[60:61], 11, v[64:65]
	v_lshl_add_u64 v[60:61], s[8:9], 0, v[60:61]
	v_lshl_add_u64 v[60:61], v[60:61], 0, v[128:129]
	v_cvt_pk_bf16_f32 v62, v70, v66
	v_cvt_pk_bf16_f32 v63, v67, v68
	global_store_dwordx2 v[60:61], v[62:63], off
	v_add_u32_e32 v60, 1, v72
	v_cvt_f32_ubyte0_e32 v60, v60
	v_mul_f32_e32 v60, v135, v60
	v_exp_f32_e32 v62, v60
	v_sub_u32_e32 v60, 0x100, v72
	v_cvt_f32_u32_e32 v60, v60
	v_mul_f32_e32 v63, v62, v70
	v_mul_f32_e32 v69, v62, v67
	v_mul_f32_e32 v60, v134, v60
	v_exp_f32_e32 v65, v60
	v_mad_i64_i32 v[60:61], s[10:11], v64, s28, v[124:125]
	v_lshl_add_u64 v[60:61], v[60:61], 0, v[128:129]
	v_mul_f32_e32 v64, v62, v66
	v_mul_f32_e32 v71, v62, v68
	v_cvt_pk_bf16_f32 v62, v63, v64
	v_cvt_pk_bf16_f32 v63, v69, v71
	global_store_dwordx2 v[60:61], v[62:63], off offset:512
	v_mul_f32_e32 v62, v65, v70
	v_mul_f32_e32 v63, v65, v66
	v_mul_f32_e32 v64, v65, v67
	v_mul_f32_e32 v65, v65, v68
	v_cvt_pk_bf16_f32 v62, v62, v63
	v_cvt_pk_bf16_f32 v63, v64, v65
	global_store_dwordx2 v[60:61], v[62:63], off offset:1024
	v_add_u32_e32 v60, 0x84, v131
	v_add_u32_e32 v64, s34, v60
	v_lshrrev_b32_e32 v61, 6, v64
	v_and_b32_e32 v68, 0xc7, v60
	v_cndmask_b32_e32 v60, v60, v61, vcc
	v_lshlrev_b32_e32 v60, 6, v60
	v_and_or_b32 v60, v60, s29, v130
	v_lshlrev_b32_e32 v60, 3, v60
	s_waitcnt vmcnt(9) lgkmcnt(6)
; DI void st4(u16* p, float a, float b, float c, float d) { u32x2 w = {cvtpk(a, b), cvtpk(c, d)}; *(u32x2*)p = w; }
; DI float ex2(float x) { return __builtin_amdgcn_exp2f(x); }
;   DI void operator()(int m, int n, f32x4 v) const { st4(dst + (size_t)m * ld + n, v[0], v[1], v[2], v[3]); }
;   DI void operator()(int m, int n, f32x4 v) const {
;     const int tl = tok0 + m, pos = tl & 4095, tsc = pos & 255;
;     const int idx = (n < 128) ? (pos >> 6) : (pos & 63), f0 = (n >> 1) & 63;
;     const float2 c0 = tab[idx * 64 + f0], c1 = tab[idx * 64 + f0 + 1];
;     const float a0 = (v[0] * c0.x - v[1] * c0.y) * 0.0625f, b0 = (v[0] * c0.y + v[1] * c0.x) * 0.0625f;
;     const float a1 = (v[2] * c1.x - v[3] * c1.y) * 0.0625f, b1 = (v[2] * c1.y + v[3] * c1.x) * 0.0625f;
;     st4(qp + (size_t)tl * 1024 + hh * 256 + n, a0, b0, a1, b1);
;     const float qf = ex2(l2f * (float)(tsc + 1)), qb = ex2(l2b * (float)(256 - tsc));
;     u16* ac = acat + (size_t)tl * 3072 + hh * 768 + n;
;     st4(ac + 256, a0 * qf, b0 * qf, a1 * qf, b1 * qf);
;     st4(ac + 512, a0 * qb, b0 * qb, a1 * qb, b1 * qb);
;   }
	v_mov_b32_e32 v60, v196
	v_mov_b32_e32 v61, v197
	v_mov_b32_e32 v62, v198
	v_mov_b32_e32 v63, v199
	v_pk_mul_f32 v[66:67], v[56:57], v[60:61]
	v_pk_mul_f32 v[56:57], v[56:57], v[60:61] op_sel:[1,0] op_sel_hi:[0,1]
	v_add_f32_e32 v56, v56, v57
	v_mul_f32_e32 v60, 0x3d800000, v56
	v_pk_mul_f32 v[56:57], v[58:59], v[62:63]
	v_sub_f32_e32 v65, v66, v67
	v_sub_f32_e32 v56, v56, v57
	v_mul_f32_e32 v61, 0x3d800000, v56
	v_pk_mul_f32 v[56:57], v[58:59], v[62:63] op_sel:[1,0] op_sel_hi:[0,1]
	v_mul_f32_e32 v66, 0x3d800000, v65
	v_add_f32_e32 v56, v56, v57
	v_ashrrev_i32_e32 v65, 31, v64
	v_mul_f32_e32 v62, 0x3d800000, v56
	v_lshlrev_b64 v[56:57], 11, v[64:65]
	v_lshl_add_u64 v[56:57], s[8:9], 0, v[56:57]
	v_lshl_add_u64 v[56:57], v[56:57], 0, v[128:129]
	v_cvt_pk_bf16_f32 v58, v66, v60
	v_cvt_pk_bf16_f32 v59, v61, v62
	global_store_dwordx2 v[56:57], v[58:59], off
	v_add_u32_e32 v56, 1, v68
	v_cvt_f32_ubyte0_e32 v56, v56
	v_mul_f32_e32 v56, v135, v56
	v_exp_f32_e32 v58, v56
	v_sub_u32_e32 v56, 0x100, v68
	v_cvt_f32_u32_e32 v56, v56
	v_mul_f32_e32 v59, v58, v66
	v_mul_f32_e32 v65, v58, v61
	v_mul_f32_e32 v56, v134, v56
	v_exp_f32_e32 v63, v56
	v_mad_i64_i32 v[56:57], s[10:11], v64, s28, v[124:125]
	v_lshl_add_u64 v[56:57], v[56:57], 0, v[128:129]
	v_mul_f32_e32 v64, v58, v60
	v_mul_f32_e32 v67, v58, v62
	v_cvt_pk_bf16_f32 v58, v59, v64
	v_cvt_pk_bf16_f32 v59, v65, v67
	global_store_dwordx2 v[56:57], v[58:59], off offset:512
	v_mul_f32_e32 v58, v63, v66
	v_mul_f32_e32 v59, v63, v60
	v_mul_f32_e32 v60, v63, v61
	v_mul_f32_e32 v61, v63, v62
	v_cvt_pk_bf16_f32 v58, v58, v59
	v_cvt_pk_bf16_f32 v59, v60, v61
	global_store_dwordx2 v[56:57], v[58:59], off offset:1024
	v_add_u32_e32 v56, 0x88, v131
	v_add_u32_e32 v60, s34, v56
	v_lshrrev_b32_e32 v57, 6, v60
	v_and_b32_e32 v64, 0xcb, v56
	v_cndmask_b32_e32 v56, v56, v57, vcc
	v_lshlrev_b32_e32 v56, 6, v56
	v_and_or_b32 v56, v56, s29, v130
	v_lshlrev_b32_e32 v56, 3, v56
	s_waitcnt vmcnt(11) lgkmcnt(5)
	v_mov_b32_e32 v56, v200
	v_mov_b32_e32 v57, v201
	v_mov_b32_e32 v58, v202
	v_mov_b32_e32 v59, v203
	v_pk_mul_f32 v[62:63], v[52:53], v[56:57]
	v_pk_mul_f32 v[52:53], v[52:53], v[56:57] op_sel:[1,0] op_sel_hi:[0,1]
	v_add_f32_e32 v52, v52, v53
	v_mul_f32_e32 v56, 0x3d800000, v52
	v_pk_mul_f32 v[52:53], v[54:55], v[58:59]
	v_sub_f32_e32 v61, v62, v63
	v_sub_f32_e32 v52, v52, v53
	v_mul_f32_e32 v57, 0x3d800000, v52
	v_pk_mul_f32 v[52:53], v[54:55], v[58:59] op_sel:[1,0] op_sel_hi:[0,1]
	v_mul_f32_e32 v62, 0x3d800000, v61
	v_add_f32_e32 v52, v52, v53
	v_ashrrev_i32_e32 v61, 31, v60
	v_mul_f32_e32 v58, 0x3d800000, v52
	v_lshlrev_b64 v[52:53], 11, v[60:61]
	v_lshl_add_u64 v[52:53], s[8:9], 0, v[52:53]
	v_lshl_add_u64 v[52:53], v[52:53], 0, v[128:129]
	v_cvt_pk_bf16_f32 v54, v62, v56
	v_cvt_pk_bf16_f32 v55, v57, v58
	global_store_dwordx2 v[52:53], v[54:55], off
	v_add_u32_e32 v52, 1, v64
	v_cvt_f32_ubyte0_e32 v52, v52
	v_mul_f32_e32 v52, v135, v52
	v_exp_f32_e32 v54, v52
	v_sub_u32_e32 v52, 0x100, v64
	v_cvt_f32_u32_e32 v52, v52
	v_mul_f32_e32 v55, v54, v62
	v_mul_f32_e32 v61, v54, v57
	v_mul_f32_e32 v52, v134, v52
	v_exp_f32_e32 v59, v52
	v_mad_i64_i32 v[52:53], s[10:11], v60, s28, v[124:125]
	v_lshl_add_u64 v[52:53], v[52:53], 0, v[128:129]
	v_mul_f32_e32 v60, v54, v56
	v_mul_f32_e32 v63, v54, v58
	v_cvt_pk_bf16_f32 v54, v55, v60
	v_cvt_pk_bf16_f32 v55, v61, v63
	global_store_dwordx2 v[52:53], v[54:55], off offset:512
	v_mul_f32_e32 v54, v59, v62
	v_mul_f32_e32 v55, v59, v56
	v_mul_f32_e32 v56, v59, v57
	v_mul_f32_e32 v57, v59, v58
	v_cvt_pk_bf16_f32 v54, v54, v55
	v_cvt_pk_bf16_f32 v55, v56, v57
	global_store_dwordx2 v[52:53], v[54:55], off offset:1024
	v_add_u32_e32 v52, 0x8c, v131
	v_add_u32_e32 v56, s34, v52
	v_lshrrev_b32_e32 v53, 6, v56
	v_and_b32_e32 v60, 0xcf, v52
	v_cndmask_b32_e32 v52, v52, v53, vcc
	v_lshlrev_b32_e32 v52, 6, v52
	v_and_or_b32 v52, v52, s29, v130
	v_lshlrev_b32_e32 v52, 3, v52
	s_waitcnt vmcnt(13) lgkmcnt(4)
	v_mov_b32_e32 v52, v204
	v_mov_b32_e32 v53, v205
	v_mov_b32_e32 v54, v206
	v_mov_b32_e32 v55, v207
	v_pk_mul_f32 v[58:59], v[48:49], v[52:53]
	v_pk_mul_f32 v[48:49], v[48:49], v[52:53] op_sel:[1,0] op_sel_hi:[0,1]
	v_add_f32_e32 v48, v48, v49
	v_mul_f32_e32 v52, 0x3d800000, v48
	v_pk_mul_f32 v[48:49], v[50:51], v[54:55]
	v_sub_f32_e32 v57, v58, v59
	v_sub_f32_e32 v48, v48, v49
	v_mul_f32_e32 v53, 0x3d800000, v48
	v_pk_mul_f32 v[48:49], v[50:51], v[54:55] op_sel:[1,0] op_sel_hi:[0,1]
	v_mul_f32_e32 v58, 0x3d800000, v57
	v_add_f32_e32 v48, v48, v49
	v_ashrrev_i32_e32 v57, 31, v56
	v_mul_f32_e32 v54, 0x3d800000, v48
	v_lshlrev_b64 v[48:49], 11, v[56:57]
	v_lshl_add_u64 v[48:49], s[8:9], 0, v[48:49]
	v_lshl_add_u64 v[48:49], v[48:49], 0, v[128:129]
	v_cvt_pk_bf16_f32 v50, v58, v52
	v_cvt_pk_bf16_f32 v51, v53, v54
	global_store_dwordx2 v[48:49], v[50:51], off
	v_add_u32_e32 v48, 1, v60
	v_cvt_f32_ubyte0_e32 v48, v48
	v_mul_f32_e32 v48, v135, v48
	v_exp_f32_e32 v50, v48
	v_sub_u32_e32 v48, 0x100, v60
	v_cvt_f32_u32_e32 v48, v48
	v_mul_f32_e32 v51, v50, v58
	v_mul_f32_e32 v57, v50, v53
	v_mul_f32_e32 v48, v134, v48
	v_exp_f32_e32 v55, v48
	v_mad_i64_i32 v[48:49], s[10:11], v56, s28, v[124:125]
	v_lshl_add_u64 v[48:49], v[48:49], 0, v[128:129]
	v_mul_f32_e32 v56, v50, v52
	v_mul_f32_e32 v59, v50, v54
	v_cvt_pk_bf16_f32 v50, v51, v56
	v_cvt_pk_bf16_f32 v51, v57, v59
	global_store_dwordx2 v[48:49], v[50:51], off offset:512
	v_mul_f32_e32 v50, v55, v58
	v_mul_f32_e32 v51, v55, v52
	v_mul_f32_e32 v52, v55, v53
	v_mul_f32_e32 v53, v55, v54
	v_cvt_pk_bf16_f32 v50, v50, v51
	v_cvt_pk_bf16_f32 v51, v52, v53
	global_store_dwordx2 v[48:49], v[50:51], off offset:1024
	v_add_u32_e32 v48, 0x90, v131
	v_add_u32_e32 v52, s34, v48
	v_lshrrev_b32_e32 v49, 6, v52
	v_and_b32_e32 v56, 0xd3, v48
	v_cndmask_b32_e32 v48, v48, v49, vcc
	v_lshlrev_b32_e32 v48, 6, v48
	v_and_or_b32 v48, v48, s29, v130
	v_lshlrev_b32_e32 v48, 3, v48
	s_waitcnt vmcnt(15) lgkmcnt(3)
; DI void st4(u16* p, float a, float b, float c, float d) { u32x2 w = {cvtpk(a, b), cvtpk(c, d)}; *(u32x2*)p = w; }
; DI float ex2(float x) { return __builtin_amdgcn_exp2f(x); }
;   DI void operator()(int m, int n, f32x4 v) const { st4(dst + (size_t)m * ld + n, v[0], v[1], v[2], v[3]); }
;   DI void operator()(int m, int n, f32x4 v) const {
;     const int tl = tok0 + m, pos = tl & 4095, tsc = pos & 255;
;     const int idx = (n < 128) ? (pos >> 6) : (pos & 63), f0 = (n >> 1) & 63;
;     const float2 c0 = tab[idx * 64 + f0], c1 = tab[idx * 64 + f0 + 1];
;     const float a0 = (v[0] * c0.x - v[1] * c0.y) * 0.0625f, b0 = (v[0] * c0.y + v[1] * c0.x) * 0.0625f;
;     const float a1 = (v[2] * c1.x - v[3] * c1.y) * 0.0625f, b1 = (v[2] * c1.y + v[3] * c1.x) * 0.0625f;
;     st4(qp + (size_t)tl * 1024 + hh * 256 + n, a0, b0, a1, b1);
;     const float qf = ex2(l2f * (float)(tsc + 1)), qb = ex2(l2b * (float)(256 - tsc));
;     u16* ac = acat + (size_t)tl * 3072 + hh * 768 + n;
;     st4(ac + 256, a0 * qf, b0 * qf, a1 * qf, b1 * qf);
;     st4(ac + 512, a0 * qb, b0 * qb, a1 * qb, b1 * qb);
;   }
	v_mov_b32_e32 v48, v208
	v_mov_b32_e32 v49, v209
	v_mov_b32_e32 v50, v210
	v_mov_b32_e32 v51, v211
	v_pk_mul_f32 v[54:55], v[44:45], v[48:49]
	v_pk_mul_f32 v[44:45], v[44:45], v[48:49] op_sel:[1,0] op_sel_hi:[0,1]
	v_add_f32_e32 v44, v44, v45
	v_mul_f32_e32 v48, 0x3d800000, v44
	v_pk_mul_f32 v[44:45], v[46:47], v[50:51]
	v_sub_f32_e32 v53, v54, v55
	v_sub_f32_e32 v44, v44, v45
	v_mul_f32_e32 v49, 0x3d800000, v44
	v_pk_mul_f32 v[44:45], v[46:47], v[50:51] op_sel:[1,0] op_sel_hi:[0,1]
	v_mul_f32_e32 v54, 0x3d800000, v53
	v_add_f32_e32 v44, v44, v45
	v_ashrrev_i32_e32 v53, 31, v52
	v_mul_f32_e32 v50, 0x3d800000, v44
	v_lshlrev_b64 v[44:45], 11, v[52:53]
	v_lshl_add_u64 v[44:45], s[8:9], 0, v[44:45]
	v_lshl_add_u64 v[44:45], v[44:45], 0, v[128:129]
	v_cvt_pk_bf16_f32 v46, v54, v48
	v_cvt_pk_bf16_f32 v47, v49, v50
	global_store_dwordx2 v[44:45], v[46:47], off
	v_add_u32_e32 v44, 1, v56
	v_cvt_f32_ubyte0_e32 v44, v44
	v_mul_f32_e32 v44, v135, v44
	v_exp_f32_e32 v46, v44
	v_sub_u32_e32 v44, 0x100, v56
	v_cvt_f32_u32_e32 v44, v44
	v_mul_f32_e32 v47, v46, v54
	v_mul_f32_e32 v53, v46, v49
	v_mul_f32_e32 v44, v134, v44
	v_exp_f32_e32 v51, v44
	v_mad_i64_i32 v[44:45], s[10:11], v52, s28, v[124:125]
	v_lshl_add_u64 v[44:45], v[44:45], 0, v[128:129]
	v_mul_f32_e32 v52, v46, v48
	v_mul_f32_e32 v55, v46, v50
	v_cvt_pk_bf16_f32 v46, v47, v52
	v_cvt_pk_bf16_f32 v47, v53, v55
	global_store_dwordx2 v[44:45], v[46:47], off offset:512
	v_mul_f32_e32 v46, v51, v54
	v_mul_f32_e32 v47, v51, v48
	v_mul_f32_e32 v48, v51, v49
	v_mul_f32_e32 v49, v51, v50
	v_cvt_pk_bf16_f32 v46, v46, v47
	v_cvt_pk_bf16_f32 v47, v48, v49
	global_store_dwordx2 v[44:45], v[46:47], off offset:1024
	v_add_u32_e32 v44, 0x94, v131
	v_add_u32_e32 v48, s34, v44
	v_lshrrev_b32_e32 v45, 6, v48
	v_and_b32_e32 v52, 0xd7, v44
	v_cndmask_b32_e32 v44, v44, v45, vcc
	v_lshlrev_b32_e32 v44, 6, v44
	v_and_or_b32 v44, v44, s29, v130
	v_lshlrev_b32_e32 v44, 3, v44
	s_waitcnt vmcnt(17) lgkmcnt(2)
	v_mov_b32_e32 v44, v212
	v_mov_b32_e32 v45, v213
	v_mov_b32_e32 v46, v214
	v_mov_b32_e32 v47, v215
	v_pk_mul_f32 v[50:51], v[40:41], v[44:45]
	v_pk_mul_f32 v[40:41], v[40:41], v[44:45] op_sel:[1,0] op_sel_hi:[0,1]
	v_add_f32_e32 v40, v40, v41
	v_mul_f32_e32 v44, 0x3d800000, v40
	v_pk_mul_f32 v[40:41], v[42:43], v[46:47]
	v_sub_f32_e32 v49, v50, v51
	v_sub_f32_e32 v40, v40, v41
	v_mul_f32_e32 v45, 0x3d800000, v40
	v_pk_mul_f32 v[40:41], v[42:43], v[46:47] op_sel:[1,0] op_sel_hi:[0,1]
	v_mul_f32_e32 v50, 0x3d800000, v49
	v_add_f32_e32 v40, v40, v41
	v_ashrrev_i32_e32 v49, 31, v48
	v_mul_f32_e32 v46, 0x3d800000, v40
	v_lshlrev_b64 v[40:41], 11, v[48:49]
	v_lshl_add_u64 v[40:41], s[8:9], 0, v[40:41]
	v_lshl_add_u64 v[40:41], v[40:41], 0, v[128:129]
	v_cvt_pk_bf16_f32 v42, v50, v44
	v_cvt_pk_bf16_f32 v43, v45, v46
	global_store_dwordx2 v[40:41], v[42:43], off
	v_add_u32_e32 v40, 1, v52
	v_cvt_f32_ubyte0_e32 v40, v40
	v_mul_f32_e32 v40, v135, v40
	v_exp_f32_e32 v42, v40
	v_sub_u32_e32 v40, 0x100, v52
	v_cvt_f32_u32_e32 v40, v40
	v_mul_f32_e32 v43, v42, v50
	v_mul_f32_e32 v49, v42, v45
	v_mul_f32_e32 v40, v134, v40
	v_exp_f32_e32 v47, v40
	v_mad_i64_i32 v[40:41], s[10:11], v48, s28, v[124:125]
	v_lshl_add_u64 v[40:41], v[40:41], 0, v[128:129]
	v_mul_f32_e32 v48, v42, v44
	v_mul_f32_e32 v51, v42, v46
	v_cvt_pk_bf16_f32 v42, v43, v48
	v_cvt_pk_bf16_f32 v43, v49, v51
	global_store_dwordx2 v[40:41], v[42:43], off offset:512
	v_mul_f32_e32 v42, v47, v50
	v_mul_f32_e32 v43, v47, v44
	v_mul_f32_e32 v44, v47, v45
	v_mul_f32_e32 v45, v47, v46
	v_cvt_pk_bf16_f32 v42, v42, v43
	v_cvt_pk_bf16_f32 v43, v44, v45
	global_store_dwordx2 v[40:41], v[42:43], off offset:1024
	v_add_u32_e32 v40, 0x98, v131
	v_add_u32_e32 v44, s34, v40
	v_lshrrev_b32_e32 v41, 6, v44
	v_and_b32_e32 v48, 0xdb, v40
	v_cndmask_b32_e32 v40, v40, v41, vcc
	v_lshlrev_b32_e32 v40, 6, v40
	v_and_or_b32 v40, v40, s29, v130
	v_lshlrev_b32_e32 v40, 3, v40
	s_waitcnt vmcnt(19) lgkmcnt(1)
	v_mov_b32_e32 v40, v216
	v_mov_b32_e32 v41, v217
	v_mov_b32_e32 v42, v218
	v_mov_b32_e32 v43, v219
	v_pk_mul_f32 v[46:47], v[36:37], v[40:41]
	v_pk_mul_f32 v[36:37], v[36:37], v[40:41] op_sel:[1,0] op_sel_hi:[0,1]
	v_add_f32_e32 v36, v36, v37
	v_mul_f32_e32 v40, 0x3d800000, v36
	v_pk_mul_f32 v[36:37], v[38:39], v[42:43]
	v_sub_f32_e32 v45, v46, v47
	v_sub_f32_e32 v36, v36, v37
	v_mul_f32_e32 v41, 0x3d800000, v36
	v_pk_mul_f32 v[36:37], v[38:39], v[42:43] op_sel:[1,0] op_sel_hi:[0,1]
	v_mul_f32_e32 v46, 0x3d800000, v45
	v_add_f32_e32 v36, v36, v37
	v_ashrrev_i32_e32 v45, 31, v44
	v_mul_f32_e32 v42, 0x3d800000, v36
	v_lshlrev_b64 v[36:37], 11, v[44:45]
	v_lshl_add_u64 v[36:37], s[8:9], 0, v[36:37]
	v_lshl_add_u64 v[36:37], v[36:37], 0, v[128:129]
	v_cvt_pk_bf16_f32 v38, v46, v40
	v_cvt_pk_bf16_f32 v39, v41, v42
	global_store_dwordx2 v[36:37], v[38:39], off
	v_add_u32_e32 v36, 1, v48
	v_cvt_f32_ubyte0_e32 v36, v36
	v_mul_f32_e32 v36, v135, v36
	v_exp_f32_e32 v38, v36
	v_sub_u32_e32 v36, 0x100, v48
	v_cvt_f32_u32_e32 v36, v36
	v_mul_f32_e32 v39, v38, v46
	v_mul_f32_e32 v45, v38, v41
	v_mul_f32_e32 v36, v134, v36
	v_exp_f32_e32 v43, v36
	v_mad_i64_i32 v[36:37], s[10:11], v44, s28, v[124:125]
	v_lshl_add_u64 v[36:37], v[36:37], 0, v[128:129]
	v_mul_f32_e32 v44, v38, v40
	v_mul_f32_e32 v47, v38, v42
	v_cvt_pk_bf16_f32 v38, v39, v44
	v_cvt_pk_bf16_f32 v39, v45, v47
	global_store_dwordx2 v[36:37], v[38:39], off offset:512
	v_mul_f32_e32 v38, v43, v46
	v_mul_f32_e32 v39, v43, v40
	v_mul_f32_e32 v40, v43, v41
	v_mul_f32_e32 v41, v43, v42
	v_cvt_pk_bf16_f32 v38, v38, v39
	v_cvt_pk_bf16_f32 v39, v40, v41
	global_store_dwordx2 v[36:37], v[38:39], off offset:1024
	v_add_u32_e32 v36, 0x9c, v131
	v_add_u32_e32 v40, s34, v36
	v_lshrrev_b32_e32 v37, 6, v40
	v_and_b32_e32 v44, 0xdf, v36
	v_cndmask_b32_e32 v36, v36, v37, vcc
	v_lshlrev_b32_e32 v36, 6, v36
	v_and_or_b32 v36, v36, s29, v130
	v_lshlrev_b32_e32 v36, 3, v36
	s_waitcnt vmcnt(21) lgkmcnt(0)
; DI void st4(u16* p, float a, float b, float c, float d) { u32x2 w = {cvtpk(a, b), cvtpk(c, d)}; *(u32x2*)p = w; }
; DI float ex2(float x) { return __builtin_amdgcn_exp2f(x); }
;   DI void operator()(int m, int n, f32x4 v) const { st4(dst + (size_t)m * ld + n, v[0], v[1], v[2], v[3]); }
;   DI void operator()(int m, int n, f32x4 v) const {
;     const int tl = tok0 + m, pos = tl & 4095, tsc = pos & 255;
;     const int idx = (n < 128) ? (pos >> 6) : (pos & 63), f0 = (n >> 1) & 63;
;     const float2 c0 = tab[idx * 64 + f0], c1 = tab[idx * 64 + f0 + 1];
;     const float a0 = (v[0] * c0.x - v[1] * c0.y) * 0.0625f, b0 = (v[0] * c0.y + v[1] * c0.x) * 0.0625f;
;     const float a1 = (v[2] * c1.x - v[3] * c1.y) * 0.0625f, b1 = (v[2] * c1.y + v[3] * c1.x) * 0.0625f;
;     st4(qp + (size_t)tl * 1024 + hh * 256 + n, a0, b0, a1, b1);
;     const float qf = ex2(l2f * (float)(tsc + 1)), qb = ex2(l2b * (float)(256 - tsc));
;     u16* ac = acat + (size_t)tl * 3072 + hh * 768 + n;
;     st4(ac + 256, a0 * qf, b0 * qf, a1 * qf, b1 * qf);
;     st4(ac + 512, a0 * qb, b0 * qb, a1 * qb, b1 * qb);
;   }
	v_mov_b32_e32 v36, v220
	v_mov_b32_e32 v37, v221
	v_mov_b32_e32 v38, v222
	v_mov_b32_e32 v39, v223
	v_pk_mul_f32 v[42:43], v[32:33], v[36:37]
	v_pk_mul_f32 v[32:33], v[32:33], v[36:37] op_sel:[1,0] op_sel_hi:[0,1]
	v_add_f32_e32 v32, v32, v33
	v_mul_f32_e32 v36, 0x3d800000, v32
	v_pk_mul_f32 v[32:33], v[34:35], v[38:39]
	v_sub_f32_e32 v41, v42, v43
	v_sub_f32_e32 v32, v32, v33
	v_mul_f32_e32 v37, 0x3d800000, v32
	v_pk_mul_f32 v[32:33], v[34:35], v[38:39] op_sel:[1,0] op_sel_hi:[0,1]
	v_mul_f32_e32 v42, 0x3d800000, v41
	v_add_f32_e32 v32, v32, v33
	v_ashrrev_i32_e32 v41, 31, v40
	v_mul_f32_e32 v38, 0x3d800000, v32
	v_lshlrev_b64 v[32:33], 11, v[40:41]
	v_lshl_add_u64 v[32:33], s[8:9], 0, v[32:33]
	v_lshl_add_u64 v[32:33], v[32:33], 0, v[128:129]
	v_cvt_pk_bf16_f32 v34, v42, v36
	v_cvt_pk_bf16_f32 v35, v37, v38
	global_store_dwordx2 v[32:33], v[34:35], off
	v_add_u32_e32 v32, 1, v44
	v_cvt_f32_ubyte0_e32 v32, v32
	v_mul_f32_e32 v32, v135, v32
	v_exp_f32_e32 v34, v32
	v_sub_u32_e32 v32, 0x100, v44
	v_cvt_f32_u32_e32 v32, v32
	v_mul_f32_e32 v35, v34, v42
	v_mul_f32_e32 v41, v34, v37
	v_mul_f32_e32 v32, v134, v32
	v_exp_f32_e32 v39, v32
	v_mad_i64_i32 v[32:33], s[10:11], v40, s28, v[124:125]
	v_lshl_add_u64 v[32:33], v[32:33], 0, v[128:129]
	v_mul_f32_e32 v40, v34, v36
	v_mul_f32_e32 v43, v34, v38
	v_cvt_pk_bf16_f32 v34, v35, v40
	v_cvt_pk_bf16_f32 v35, v41, v43
	global_store_dwordx2 v[32:33], v[34:35], off offset:512
	v_mul_f32_e32 v34, v39, v42
	v_mul_f32_e32 v35, v39, v36
	v_mul_f32_e32 v36, v39, v37
	v_mul_f32_e32 v37, v39, v38
	v_cvt_pk_bf16_f32 v34, v34, v35
	v_cvt_pk_bf16_f32 v35, v36, v37
	global_store_dwordx2 v[32:33], v[34:35], off offset:1024
	v_add_u32_e32 v33, 0xa0, v131
	v_add_u32_e32 v32, s34, v33
	v_lshrrev_b32_e32 v34, 6, v32
	v_and_b32_e32 v40, 0xe3, v33
	v_cndmask_b32_e32 v33, v33, v34, vcc
	v_lshlrev_b32_e32 v33, 6, v33
	s_waitcnt lgkmcnt(0)
	ds_write2_b32 v132, v8, v12 offset1:16
	ds_write2_b32 v132, v9, v13 offset0:68 offset1:84
	ds_write2_b32 v132, v10, v14 offset0:136 offset1:152
	ds_write2_b32 v132, v11, v15 offset0:204 offset1:220
	ds_write2_b32 v132, v24, v28 offset0:32 offset1:48
	ds_write2_b32 v132, v25, v29 offset0:100 offset1:116
	ds_write2_b32 v132, v26, v30 offset0:168 offset1:184
	ds_write2_b32 v132, v27, v31 offset0:236 offset1:252
	ds_write2_b32 v133, v0, v4 offset0:64 offset1:80
	ds_write2_b32 v133, v1, v5 offset0:132 offset1:148
	ds_write2_b32 v133, v2, v6 offset0:200 offset1:216
	ds_write2_b32 v137, v3, v7 offset0:12 offset1:28
	ds_write2_b32 v133, v16, v20 offset0:96 offset1:112
	ds_write2_b32 v133, v17, v21 offset0:164 offset1:180
	ds_write2_b32 v133, v18, v22 offset0:232 offset1:248
	ds_write2_b32 v137, v19, v23 offset0:44 offset1:60
	v_and_or_b32 v33, v33, s29, v130
	s_waitcnt lgkmcnt(0)
	v_lshlrev_b32_e32 v33, 3, v33
	ds_read_b128 v[28:31], v136
	ds_read_b128 v[24:27], v136 offset:1088
	ds_read_b128 v[20:23], v136 offset:2176
	ds_read_b128 v[16:19], v136 offset:3264
	ds_read_b128 v[12:15], v136 offset:4352
	ds_read_b128 v[8:11], v136 offset:5440
	ds_read_b128 v[4:7], v136 offset:6528
	ds_read_b128 v[0:3], v136 offset:7616
	global_load_dwordx4 v[192:195], v33, s[84:85]
	v_add_u32_e32 v224, v33, v225
	global_load_dwordx4 v[196:199], v224, s[84:85]
	v_add_u32_e32 v224, v224, v225
	global_load_dwordx4 v[200:203], v224, s[84:85]
	v_add_u32_e32 v224, v224, v225
	global_load_dwordx4 v[204:207], v224, s[84:85]
	v_add_u32_e32 v224, v224, v225
	global_load_dwordx4 v[208:211], v224, s[84:85]
	v_add_u32_e32 v224, v224, v225
	global_load_dwordx4 v[212:215], v224, s[84:85]
	v_add_u32_e32 v224, v224, v225
	global_load_dwordx4 v[216:219], v224, s[84:85]
	v_add_u32_e32 v224, v224, v225
	global_load_dwordx4 v[220:223], v224, s[84:85]
	s_waitcnt vmcnt(7) lgkmcnt(7)
	v_mov_b32_e32 v34, v192
	v_mov_b32_e32 v35, v193
	v_mov_b32_e32 v36, v194
	v_mov_b32_e32 v37, v195
	v_pk_mul_f32 v[38:39], v[28:29], v[34:35]
	v_pk_mul_f32 v[28:29], v[28:29], v[34:35] op_sel:[1,0] op_sel_hi:[0,1]
	v_add_f32_e32 v28, v28, v29
	v_mul_f32_e32 v34, 0x3d800000, v28
	v_pk_mul_f32 v[28:29], v[30:31], v[36:37]
	v_sub_f32_e32 v33, v38, v39
	v_sub_f32_e32 v28, v28, v29
	v_mul_f32_e32 v35, 0x3d800000, v28
	v_pk_mul_f32 v[28:29], v[30:31], v[36:37] op_sel:[1,0] op_sel_hi:[0,1]
	v_mul_f32_e32 v38, 0x3d800000, v33
	v_add_f32_e32 v28, v28, v29
	v_ashrrev_i32_e32 v33, 31, v32
	v_mul_f32_e32 v36, 0x3d800000, v28
	v_lshlrev_b64 v[28:29], 11, v[32:33]
	v_lshl_add_u64 v[28:29], s[8:9], 0, v[28:29]
	v_lshl_add_u64 v[28:29], v[28:29], 0, v[128:129]
	v_cvt_pk_bf16_f32 v30, v38, v34
	v_cvt_pk_bf16_f32 v31, v35, v36
	global_store_dwordx2 v[28:29], v[30:31], off
	v_add_u32_e32 v28, 1, v40
	v_cvt_f32_ubyte0_e32 v28, v28
	v_mul_f32_e32 v28, v135, v28
	v_exp_f32_e32 v30, v28
	v_sub_u32_e32 v28, 0x100, v40
	v_cvt_f32_u32_e32 v28, v28
	v_mul_f32_e32 v31, v30, v38
	v_mul_f32_e32 v37, v30, v35
	v_mul_f32_e32 v28, v134, v28
	v_exp_f32_e32 v33, v28
	v_mad_i64_i32 v[28:29], s[10:11], v32, s28, v[124:125]
	v_lshl_add_u64 v[28:29], v[28:29], 0, v[128:129]
	v_mul_f32_e32 v32, v30, v34
	v_mul_f32_e32 v39, v30, v36
	v_cvt_pk_bf16_f32 v30, v31, v32
	v_cvt_pk_bf16_f32 v31, v37, v39
	global_store_dwordx2 v[28:29], v[30:31], off offset:512
	v_mul_f32_e32 v30, v33, v38
	v_mul_f32_e32 v31, v33, v34
	v_mul_f32_e32 v32, v33, v35
	v_mul_f32_e32 v33, v33, v36
	v_cvt_pk_bf16_f32 v30, v30, v31
	v_cvt_pk_bf16_f32 v31, v32, v33
	global_store_dwordx2 v[28:29], v[30:31], off offset:1024
	v_add_u32_e32 v28, 0xa4, v131
	v_add_u32_e32 v32, s34, v28
	v_lshrrev_b32_e32 v29, 6, v32
	v_and_b32_e32 v36, 0xe7, v28
	v_cndmask_b32_e32 v28, v28, v29, vcc
	v_lshlrev_b32_e32 v28, 6, v28
	v_and_or_b32 v28, v28, s29, v130
	v_lshlrev_b32_e32 v28, 3, v28
	s_waitcnt vmcnt(9) lgkmcnt(6)
; DI void st4(u16* p, float a, float b, float c, float d) { u32x2 w = {cvtpk(a, b), cvtpk(c, d)}; *(u32x2*)p = w; }
; DI float ex2(float x) { return __builtin_amdgcn_exp2f(x); }
;   DI void operator()(int m, int n, f32x4 v) const { st4(dst + (size_t)m * ld + n, v[0], v[1], v[2], v[3]); }
;   DI void operator()(int m, int n, f32x4 v) const {
;     const int tl = tok0 + m, pos = tl & 4095, tsc = pos & 255;
;     const int idx = (n < 128) ? (pos >> 6) : (pos & 63), f0 = (n >> 1) & 63;
;     const float2 c0 = tab[idx * 64 + f0], c1 = tab[idx * 64 + f0 + 1];
;     const float a0 = (v[0] * c0.x - v[1] * c0.y) * 0.0625f, b0 = (v[0] * c0.y + v[1] * c0.x) * 0.0625f;
;     const float a1 = (v[2] * c1.x - v[3] * c1.y) * 0.0625f, b1 = (v[2] * c1.y + v[3] * c1.x) * 0.0625f;
;     st4(qp + (size_t)tl * 1024 + hh * 256 + n, a0, b0, a1, b1);
;     const float qf = ex2(l2f * (float)(tsc + 1)), qb = ex2(l2b * (float)(256 - tsc));
;     u16* ac = acat + (size_t)tl * 3072 + hh * 768 + n;
;     st4(ac + 256, a0 * qf, b0 * qf, a1 * qf, b1 * qf);
;     st4(ac + 512, a0 * qb, b0 * qb, a1 * qb, b1 * qb);
;   }
	v_mov_b32_e32 v28, v196
	v_mov_b32_e32 v29, v197
	v_mov_b32_e32 v30, v198
	v_mov_b32_e32 v31, v199
	v_pk_mul_f32 v[34:35], v[24:25], v[28:29]
	v_pk_mul_f32 v[24:25], v[24:25], v[28:29] op_sel:[1,0] op_sel_hi:[0,1]
	v_add_f32_e32 v24, v24, v25
	v_mul_f32_e32 v28, 0x3d800000, v24
	v_pk_mul_f32 v[24:25], v[26:27], v[30:31]
	v_sub_f32_e32 v33, v34, v35
	v_sub_f32_e32 v24, v24, v25
	v_mul_f32_e32 v29, 0x3d800000, v24
	v_pk_mul_f32 v[24:25], v[26:27], v[30:31] op_sel:[1,0] op_sel_hi:[0,1]
	v_mul_f32_e32 v34, 0x3d800000, v33
	v_add_f32_e32 v24, v24, v25
	v_ashrrev_i32_e32 v33, 31, v32
	v_mul_f32_e32 v30, 0x3d800000, v24
	v_lshlrev_b64 v[24:25], 11, v[32:33]
	v_lshl_add_u64 v[24:25], s[8:9], 0, v[24:25]
	v_lshl_add_u64 v[24:25], v[24:25], 0, v[128:129]
	v_cvt_pk_bf16_f32 v26, v34, v28
	v_cvt_pk_bf16_f32 v27, v29, v30
	global_store_dwordx2 v[24:25], v[26:27], off
	v_add_u32_e32 v24, 1, v36
	v_cvt_f32_ubyte0_e32 v24, v24
	v_mul_f32_e32 v24, v135, v24
	v_exp_f32_e32 v26, v24
	v_sub_u32_e32 v24, 0x100, v36
	v_cvt_f32_u32_e32 v24, v24
	v_mul_f32_e32 v27, v26, v34
	v_mul_f32_e32 v33, v26, v29
	v_mul_f32_e32 v24, v134, v24
	v_exp_f32_e32 v31, v24
	v_mad_i64_i32 v[24:25], s[10:11], v32, s28, v[124:125]
	v_lshl_add_u64 v[24:25], v[24:25], 0, v[128:129]
	v_mul_f32_e32 v32, v26, v28
	v_mul_f32_e32 v35, v26, v30
	v_cvt_pk_bf16_f32 v26, v27, v32
	v_cvt_pk_bf16_f32 v27, v33, v35
	global_store_dwordx2 v[24:25], v[26:27], off offset:512
	v_mul_f32_e32 v26, v31, v34
	v_mul_f32_e32 v27, v31, v28
	v_mul_f32_e32 v28, v31, v29
	v_mul_f32_e32 v29, v31, v30
	v_cvt_pk_bf16_f32 v26, v26, v27
	v_cvt_pk_bf16_f32 v27, v28, v29
	global_store_dwordx2 v[24:25], v[26:27], off offset:1024
	v_add_u32_e32 v24, 0xa8, v131
	v_add_u32_e32 v28, s34, v24
	v_lshrrev_b32_e32 v25, 6, v28
	v_and_b32_e32 v32, 0xeb, v24
	v_cndmask_b32_e32 v24, v24, v25, vcc
	v_lshlrev_b32_e32 v24, 6, v24
	v_and_or_b32 v24, v24, s29, v130
	v_lshlrev_b32_e32 v24, 3, v24
	s_waitcnt vmcnt(11) lgkmcnt(5)
	v_mov_b32_e32 v24, v200
	v_mov_b32_e32 v25, v201
	v_mov_b32_e32 v26, v202
	v_mov_b32_e32 v27, v203
	v_pk_mul_f32 v[30:31], v[20:21], v[24:25]
	v_pk_mul_f32 v[20:21], v[20:21], v[24:25] op_sel:[1,0] op_sel_hi:[0,1]
	v_add_f32_e32 v20, v20, v21
	v_mul_f32_e32 v24, 0x3d800000, v20
	v_pk_mul_f32 v[20:21], v[22:23], v[26:27]
	v_sub_f32_e32 v29, v30, v31
	v_sub_f32_e32 v20, v20, v21
	v_mul_f32_e32 v25, 0x3d800000, v20
	v_pk_mul_f32 v[20:21], v[22:23], v[26:27] op_sel:[1,0] op_sel_hi:[0,1]
	v_mul_f32_e32 v30, 0x3d800000, v29
	v_add_f32_e32 v20, v20, v21
	v_ashrrev_i32_e32 v29, 31, v28
	v_mul_f32_e32 v26, 0x3d800000, v20
	v_lshlrev_b64 v[20:21], 11, v[28:29]
	v_lshl_add_u64 v[20:21], s[8:9], 0, v[20:21]
	v_lshl_add_u64 v[20:21], v[20:21], 0, v[128:129]
	v_cvt_pk_bf16_f32 v22, v30, v24
	v_cvt_pk_bf16_f32 v23, v25, v26
	global_store_dwordx2 v[20:21], v[22:23], off
	v_add_u32_e32 v20, 1, v32
	v_cvt_f32_ubyte0_e32 v20, v20
	v_mul_f32_e32 v20, v135, v20
	v_exp_f32_e32 v22, v20
	v_sub_u32_e32 v20, 0x100, v32
	v_cvt_f32_u32_e32 v20, v20
	v_mul_f32_e32 v23, v22, v30
	v_mul_f32_e32 v29, v22, v25
	v_mul_f32_e32 v20, v134, v20
	v_exp_f32_e32 v27, v20
	v_mad_i64_i32 v[20:21], s[10:11], v28, s28, v[124:125]
	v_lshl_add_u64 v[20:21], v[20:21], 0, v[128:129]
	v_mul_f32_e32 v28, v22, v24
	v_mul_f32_e32 v31, v22, v26
	v_cvt_pk_bf16_f32 v22, v23, v28
	v_cvt_pk_bf16_f32 v23, v29, v31
	global_store_dwordx2 v[20:21], v[22:23], off offset:512
	v_mul_f32_e32 v22, v27, v30
	v_mul_f32_e32 v23, v27, v24
	v_mul_f32_e32 v24, v27, v25
	v_mul_f32_e32 v25, v27, v26
	v_cvt_pk_bf16_f32 v22, v22, v23
	v_cvt_pk_bf16_f32 v23, v24, v25
	global_store_dwordx2 v[20:21], v[22:23], off offset:1024
	v_add_u32_e32 v20, 0xac, v131
	v_add_u32_e32 v24, s34, v20
	v_lshrrev_b32_e32 v21, 6, v24
	v_and_b32_e32 v28, 0xef, v20
	v_cndmask_b32_e32 v20, v20, v21, vcc
	v_lshlrev_b32_e32 v20, 6, v20
	v_and_or_b32 v20, v20, s29, v130
	v_lshlrev_b32_e32 v20, 3, v20
	s_waitcnt vmcnt(13) lgkmcnt(4)
	v_mov_b32_e32 v20, v204
	v_mov_b32_e32 v21, v205
	v_mov_b32_e32 v22, v206
	v_mov_b32_e32 v23, v207
	v_pk_mul_f32 v[26:27], v[16:17], v[20:21]
	v_pk_mul_f32 v[16:17], v[16:17], v[20:21] op_sel:[1,0] op_sel_hi:[0,1]
	v_add_f32_e32 v16, v16, v17
	v_mul_f32_e32 v20, 0x3d800000, v16
	v_pk_mul_f32 v[16:17], v[18:19], v[22:23]
	v_sub_f32_e32 v25, v26, v27
	v_sub_f32_e32 v16, v16, v17
	v_mul_f32_e32 v21, 0x3d800000, v16
	v_pk_mul_f32 v[16:17], v[18:19], v[22:23] op_sel:[1,0] op_sel_hi:[0,1]
	v_mul_f32_e32 v26, 0x3d800000, v25
	v_add_f32_e32 v16, v16, v17
	v_ashrrev_i32_e32 v25, 31, v24
	v_mul_f32_e32 v22, 0x3d800000, v16
	v_lshlrev_b64 v[16:17], 11, v[24:25]
	v_lshl_add_u64 v[16:17], s[8:9], 0, v[16:17]
	v_lshl_add_u64 v[16:17], v[16:17], 0, v[128:129]
	v_cvt_pk_bf16_f32 v18, v26, v20
	v_cvt_pk_bf16_f32 v19, v21, v22
	global_store_dwordx2 v[16:17], v[18:19], off
	v_add_u32_e32 v16, 1, v28
	v_cvt_f32_ubyte0_e32 v16, v16
	v_mul_f32_e32 v16, v135, v16
	v_exp_f32_e32 v18, v16
	v_sub_u32_e32 v16, 0x100, v28
	v_cvt_f32_u32_e32 v16, v16
	v_mul_f32_e32 v19, v18, v26
	v_mul_f32_e32 v25, v18, v21
	v_mul_f32_e32 v16, v134, v16
	v_exp_f32_e32 v23, v16
	v_mad_i64_i32 v[16:17], s[10:11], v24, s28, v[124:125]
	v_lshl_add_u64 v[16:17], v[16:17], 0, v[128:129]
	v_mul_f32_e32 v24, v18, v20
	v_mul_f32_e32 v27, v18, v22
	v_cvt_pk_bf16_f32 v18, v19, v24
	v_cvt_pk_bf16_f32 v19, v25, v27
	global_store_dwordx2 v[16:17], v[18:19], off offset:512
	v_mul_f32_e32 v18, v23, v26
	v_mul_f32_e32 v19, v23, v20
	v_mul_f32_e32 v20, v23, v21
	v_mul_f32_e32 v21, v23, v22
	v_cvt_pk_bf16_f32 v18, v18, v19
	v_cvt_pk_bf16_f32 v19, v20, v21
	global_store_dwordx2 v[16:17], v[18:19], off offset:1024
	v_add_u32_e32 v16, 0xb0, v131
	v_add_u32_e32 v20, s34, v16
	v_lshrrev_b32_e32 v17, 6, v20
	v_and_b32_e32 v24, 0xf3, v16
	v_cndmask_b32_e32 v16, v16, v17, vcc
	v_lshlrev_b32_e32 v16, 6, v16
	v_and_or_b32 v16, v16, s29, v130
	v_lshlrev_b32_e32 v16, 3, v16
	s_waitcnt vmcnt(15) lgkmcnt(3)
; DI void st4(u16* p, float a, float b, float c, float d) { u32x2 w = {cvtpk(a, b), cvtpk(c, d)}; *(u32x2*)p = w; }
; DI float ex2(float x) { return __builtin_amdgcn_exp2f(x); }
;   DI void operator()(int m, int n, f32x4 v) const { st4(dst + (size_t)m * ld + n, v[0], v[1], v[2], v[3]); }
;   DI void operator()(int m, int n, f32x4 v) const {
;     const int tl = tok0 + m, pos = tl & 4095, tsc = pos & 255;
;     const int idx = (n < 128) ? (pos >> 6) : (pos & 63), f0 = (n >> 1) & 63;
;     const float2 c0 = tab[idx * 64 + f0], c1 = tab[idx * 64 + f0 + 1];
;     const float a0 = (v[0] * c0.x - v[1] * c0.y) * 0.0625f, b0 = (v[0] * c0.y + v[1] * c0.x) * 0.0625f;
;     const float a1 = (v[2] * c1.x - v[3] * c1.y) * 0.0625f, b1 = (v[2] * c1.y + v[3] * c1.x) * 0.0625f;
;     st4(qp + (size_t)tl * 1024 + hh * 256 + n, a0, b0, a1, b1);
;     const float qf = ex2(l2f * (float)(tsc + 1)), qb = ex2(l2b * (float)(256 - tsc));
;     u16* ac = acat + (size_t)tl * 3072 + hh * 768 + n;
;     st4(ac + 256, a0 * qf, b0 * qf, a1 * qf, b1 * qf);
;     st4(ac + 512, a0 * qb, b0 * qb, a1 * qb, b1 * qb);
;   }
	v_mov_b32_e32 v16, v208
	v_mov_b32_e32 v17, v209
	v_mov_b32_e32 v18, v210
	v_mov_b32_e32 v19, v211
	v_pk_mul_f32 v[22:23], v[12:13], v[16:17]
	v_pk_mul_f32 v[12:13], v[12:13], v[16:17] op_sel:[1,0] op_sel_hi:[0,1]
	v_add_f32_e32 v12, v12, v13
	v_mul_f32_e32 v16, 0x3d800000, v12
	v_pk_mul_f32 v[12:13], v[14:15], v[18:19]
	v_sub_f32_e32 v21, v22, v23
	v_sub_f32_e32 v12, v12, v13
	v_mul_f32_e32 v17, 0x3d800000, v12
	v_pk_mul_f32 v[12:13], v[14:15], v[18:19] op_sel:[1,0] op_sel_hi:[0,1]
	v_mul_f32_e32 v22, 0x3d800000, v21
	v_add_f32_e32 v12, v12, v13
	v_ashrrev_i32_e32 v21, 31, v20
	v_mul_f32_e32 v18, 0x3d800000, v12
	v_lshlrev_b64 v[12:13], 11, v[20:21]
	v_lshl_add_u64 v[12:13], s[8:9], 0, v[12:13]
	v_lshl_add_u64 v[12:13], v[12:13], 0, v[128:129]
	v_cvt_pk_bf16_f32 v14, v22, v16
	v_cvt_pk_bf16_f32 v15, v17, v18
	global_store_dwordx2 v[12:13], v[14:15], off
	v_add_u32_e32 v12, 1, v24
	v_cvt_f32_ubyte0_e32 v12, v12
	v_mul_f32_e32 v12, v135, v12
	v_exp_f32_e32 v14, v12
	v_sub_u32_e32 v12, 0x100, v24
	v_cvt_f32_u32_e32 v12, v12
	v_mul_f32_e32 v15, v14, v22
	v_mul_f32_e32 v21, v14, v17
	v_mul_f32_e32 v12, v134, v12
	v_exp_f32_e32 v19, v12
	v_mad_i64_i32 v[12:13], s[10:11], v20, s28, v[124:125]
	v_lshl_add_u64 v[12:13], v[12:13], 0, v[128:129]
	v_mul_f32_e32 v20, v14, v16
	v_mul_f32_e32 v23, v14, v18
	v_cvt_pk_bf16_f32 v14, v15, v20
	v_cvt_pk_bf16_f32 v15, v21, v23
	global_store_dwordx2 v[12:13], v[14:15], off offset:512
	v_mul_f32_e32 v14, v19, v22
	v_mul_f32_e32 v15, v19, v16
	v_mul_f32_e32 v16, v19, v17
	v_mul_f32_e32 v17, v19, v18
	v_cvt_pk_bf16_f32 v14, v14, v15
	v_cvt_pk_bf16_f32 v15, v16, v17
	global_store_dwordx2 v[12:13], v[14:15], off offset:1024
	v_add_u32_e32 v12, 0xb4, v131
	v_add_u32_e32 v16, s34, v12
	v_lshrrev_b32_e32 v13, 6, v16
	v_and_b32_e32 v20, 0xf7, v12
	v_cndmask_b32_e32 v12, v12, v13, vcc
	v_lshlrev_b32_e32 v12, 6, v12
	v_and_or_b32 v12, v12, s29, v130
	v_lshlrev_b32_e32 v12, 3, v12
	s_waitcnt vmcnt(17) lgkmcnt(2)
	v_mov_b32_e32 v12, v212
	v_mov_b32_e32 v13, v213
	v_mov_b32_e32 v14, v214
	v_mov_b32_e32 v15, v215
	v_pk_mul_f32 v[18:19], v[8:9], v[12:13]
	v_pk_mul_f32 v[8:9], v[8:9], v[12:13] op_sel:[1,0] op_sel_hi:[0,1]
	v_add_f32_e32 v8, v8, v9
	v_mul_f32_e32 v12, 0x3d800000, v8
	v_pk_mul_f32 v[8:9], v[10:11], v[14:15]
	v_sub_f32_e32 v17, v18, v19
	v_sub_f32_e32 v8, v8, v9
	v_mul_f32_e32 v13, 0x3d800000, v8
	v_pk_mul_f32 v[8:9], v[10:11], v[14:15] op_sel:[1,0] op_sel_hi:[0,1]
	v_mul_f32_e32 v18, 0x3d800000, v17
	v_add_f32_e32 v8, v8, v9
	v_ashrrev_i32_e32 v17, 31, v16
	v_mul_f32_e32 v14, 0x3d800000, v8
	v_lshlrev_b64 v[8:9], 11, v[16:17]
	v_lshl_add_u64 v[8:9], s[8:9], 0, v[8:9]
	v_lshl_add_u64 v[8:9], v[8:9], 0, v[128:129]
	v_cvt_pk_bf16_f32 v10, v18, v12
	v_cvt_pk_bf16_f32 v11, v13, v14
	global_store_dwordx2 v[8:9], v[10:11], off
	v_add_u32_e32 v8, 1, v20
	v_cvt_f32_ubyte0_e32 v8, v8
	v_mul_f32_e32 v8, v135, v8
	v_exp_f32_e32 v10, v8
	v_sub_u32_e32 v8, 0x100, v20
	v_cvt_f32_u32_e32 v8, v8
	v_mul_f32_e32 v11, v10, v18
	v_mul_f32_e32 v17, v10, v13
	v_mul_f32_e32 v8, v134, v8
	v_exp_f32_e32 v15, v8
	v_mad_i64_i32 v[8:9], s[10:11], v16, s28, v[124:125]
	v_lshl_add_u64 v[8:9], v[8:9], 0, v[128:129]
	v_mul_f32_e32 v16, v10, v12
	v_mul_f32_e32 v19, v10, v14
	v_cvt_pk_bf16_f32 v10, v11, v16
	v_cvt_pk_bf16_f32 v11, v17, v19
	global_store_dwordx2 v[8:9], v[10:11], off offset:512
	v_mul_f32_e32 v10, v15, v18
	v_mul_f32_e32 v11, v15, v12
	v_mul_f32_e32 v12, v15, v13
	v_mul_f32_e32 v13, v15, v14
	v_cvt_pk_bf16_f32 v10, v10, v11
	v_cvt_pk_bf16_f32 v11, v12, v13
	global_store_dwordx2 v[8:9], v[10:11], off offset:1024
	v_add_u32_e32 v8, 0xb8, v131
	v_add_u32_e32 v12, s34, v8
	v_lshrrev_b32_e32 v9, 6, v12
	v_and_b32_e32 v16, 0xfb, v8
	v_cndmask_b32_e32 v8, v8, v9, vcc
	v_lshlrev_b32_e32 v8, 6, v8
	v_and_or_b32 v8, v8, s29, v130
	v_lshlrev_b32_e32 v8, 3, v8
	s_waitcnt vmcnt(19) lgkmcnt(1)
; DI void st4(u16* p, float a, float b, float c, float d) { u32x2 w = {cvtpk(a, b), cvtpk(c, d)}; *(u32x2*)p = w; }
; DI float ex2(float x) { return __builtin_amdgcn_exp2f(x); }
;   DI void operator()(int m, int n, f32x4 v) const { st4(dst + (size_t)m * ld + n, v[0], v[1], v[2], v[3]); }
;   DI void operator()(int m, int n, f32x4 v) const {
;     const int tl = tok0 + m, pos = tl & 4095, tsc = pos & 255;
;     const int idx = (n < 128) ? (pos >> 6) : (pos & 63), f0 = (n >> 1) & 63;
;     const float2 c0 = tab[idx * 64 + f0], c1 = tab[idx * 64 + f0 + 1];
;     const float a0 = (v[0] * c0.x - v[1] * c0.y) * 0.0625f, b0 = (v[0] * c0.y + v[1] * c0.x) * 0.0625f;
;     const float a1 = (v[2] * c1.x - v[3] * c1.y) * 0.0625f, b1 = (v[2] * c1.y + v[3] * c1.x) * 0.0625f;
;     st4(qp + (size_t)tl * 1024 + hh * 256 + n, a0, b0, a1, b1);
;     const float qf = ex2(l2f * (float)(tsc + 1)), qb = ex2(l2b * (float)(256 - tsc));
;     u16* ac = acat + (size_t)tl * 3072 + hh * 768 + n;
;     st4(ac + 256, a0 * qf, b0 * qf, a1 * qf, b1 * qf);
;     st4(ac + 512, a0 * qb, b0 * qb, a1 * qb, b1 * qb);
;   }
	v_mov_b32_e32 v8, v216
	v_mov_b32_e32 v9, v217
	v_mov_b32_e32 v10, v218
	v_mov_b32_e32 v11, v219
	v_pk_mul_f32 v[14:15], v[4:5], v[8:9]
	v_pk_mul_f32 v[4:5], v[4:5], v[8:9] op_sel:[1,0] op_sel_hi:[0,1]
	v_add_f32_e32 v4, v4, v5
	v_mul_f32_e32 v8, 0x3d800000, v4
	v_pk_mul_f32 v[4:5], v[6:7], v[10:11]
	v_sub_f32_e32 v13, v14, v15
	v_sub_f32_e32 v4, v4, v5
	v_mul_f32_e32 v9, 0x3d800000, v4
	v_pk_mul_f32 v[4:5], v[6:7], v[10:11] op_sel:[1,0] op_sel_hi:[0,1]
	v_mul_f32_e32 v14, 0x3d800000, v13
	v_add_f32_e32 v4, v4, v5
	v_ashrrev_i32_e32 v13, 31, v12
	v_mul_f32_e32 v10, 0x3d800000, v4
	v_lshlrev_b64 v[4:5], 11, v[12:13]
	v_lshl_add_u64 v[4:5], s[8:9], 0, v[4:5]
	v_lshl_add_u64 v[4:5], v[4:5], 0, v[128:129]
	v_cvt_pk_bf16_f32 v6, v14, v8
	v_cvt_pk_bf16_f32 v7, v9, v10
	global_store_dwordx2 v[4:5], v[6:7], off
	v_add_u32_e32 v4, 1, v16
	v_cvt_f32_ubyte0_e32 v4, v4
	v_mul_f32_e32 v4, v135, v4
	v_exp_f32_e32 v6, v4
	v_sub_u32_e32 v4, 0x100, v16
	v_cvt_f32_u32_e32 v4, v4
	v_mul_f32_e32 v7, v6, v14
	v_mul_f32_e32 v13, v6, v9
	v_mul_f32_e32 v4, v134, v4
	v_exp_f32_e32 v11, v4
	v_mad_i64_i32 v[4:5], s[10:11], v12, s28, v[124:125]
	v_lshl_add_u64 v[4:5], v[4:5], 0, v[128:129]
	v_mul_f32_e32 v12, v6, v8
	v_mul_f32_e32 v15, v6, v10
	v_cvt_pk_bf16_f32 v6, v7, v12
	v_cvt_pk_bf16_f32 v7, v13, v15
	global_store_dwordx2 v[4:5], v[6:7], off offset:512
	v_mul_f32_e32 v6, v11, v14
	v_mul_f32_e32 v7, v11, v8
	v_mul_f32_e32 v8, v11, v9
	v_add_u32_e32 v12, 0xbc, v131
	v_mul_f32_e32 v9, v11, v10
	v_cvt_pk_bf16_f32 v6, v6, v7
	v_cvt_pk_bf16_f32 v7, v8, v9
	v_add_u32_e32 v8, s34, v12
	global_store_dwordx2 v[4:5], v[6:7], off offset:1024
	v_lshrrev_b32_e32 v4, 6, v8
	v_cndmask_b32_e32 v4, v12, v4, vcc
	v_lshlrev_b32_e32 v4, 6, v4
	v_and_or_b32 v4, v4, s29, v130
	v_lshlrev_b32_e32 v4, 3, v4
	s_andn2_b64 vcc, exec, s[74:75]
	s_waitcnt vmcnt(21) lgkmcnt(0)
	v_mov_b32_e32 v4, v220
	v_mov_b32_e32 v5, v221
	v_mov_b32_e32 v6, v222
	v_mov_b32_e32 v7, v223
	v_pk_mul_f32 v[10:11], v[0:1], v[4:5]
	v_pk_mul_f32 v[0:1], v[0:1], v[4:5] op_sel:[1,0] op_sel_hi:[0,1]
	v_add_f32_e32 v0, v0, v1
	v_mul_f32_e32 v4, 0x3d800000, v0
	v_pk_mul_f32 v[0:1], v[2:3], v[6:7]
	v_sub_f32_e32 v9, v10, v11
	v_sub_f32_e32 v0, v0, v1
	v_mul_f32_e32 v5, 0x3d800000, v0
	v_pk_mul_f32 v[0:1], v[2:3], v[6:7] op_sel:[1,0] op_sel_hi:[0,1]
	v_mul_f32_e32 v10, 0x3d800000, v9
	v_add_f32_e32 v0, v0, v1
	v_ashrrev_i32_e32 v9, 31, v8
	v_mul_f32_e32 v6, 0x3d800000, v0
	v_lshlrev_b64 v[0:1], 11, v[8:9]
	v_lshl_add_u64 v[0:1], s[8:9], 0, v[0:1]
	v_lshl_add_u64 v[0:1], v[0:1], 0, v[128:129]
	v_cvt_pk_bf16_f32 v2, v10, v4
	v_cvt_pk_bf16_f32 v3, v5, v6
	global_store_dwordx2 v[0:1], v[2:3], off
	v_add_u32_sdwa v0, v12, v252 dst_sel:DWORD dst_unused:UNUSED_PAD src0_sel:BYTE_0 src1_sel:DWORD
	v_cvt_f32_u32_e32 v0, v0
	v_mul_f32_e32 v0, v135, v0
	v_exp_f32_e32 v2, v0
	v_sub_u32_sdwa v0, s92, v12 dst_sel:DWORD dst_unused:UNUSED_PAD src0_sel:DWORD src1_sel:BYTE_0
	v_cvt_f32_u32_e32 v0, v0
	v_mul_f32_e32 v3, v2, v10
	v_mul_f32_e32 v9, v2, v5
	v_mul_f32_e32 v0, v134, v0
	v_exp_f32_e32 v7, v0
	v_mad_i64_i32 v[0:1], s[8:9], v8, s28, v[124:125]
	v_lshl_add_u64 v[0:1], v[0:1], 0, v[128:129]
	v_mul_f32_e32 v8, v2, v4
	v_mul_f32_e32 v11, v2, v6
	v_cvt_pk_bf16_f32 v2, v3, v8
	v_cvt_pk_bf16_f32 v3, v9, v11
	global_store_dwordx2 v[0:1], v[2:3], off offset:512
	v_mul_f32_e32 v2, v7, v10
	v_mul_f32_e32 v3, v7, v4
	v_mul_f32_e32 v4, v7, v5
	v_mul_f32_e32 v5, v7, v6
	v_cvt_pk_bf16_f32 v2, v2, v3
	v_cvt_pk_bf16_f32 v3, v4, v5
	global_store_dwordx2 v[0:1], v[2:3], off offset:1024
	s_waitcnt lgkmcnt(0)
	s_cbranch_vccz .LBB0_262
	s_and_b64 vcc, exec, s[76:77]
	s_cbranch_vccz .LBB0_205
